# K-loop load segments: fragment ds_reads issued before pointer arithmetic (24 segments) + m0/address-add reorder, on top of v10
# speedup vs baseline: 1.0127x; 1.0127x over previous
; #define PG8_STAGE(bufoff, gbase, voff) do { _Pragma("unroll") for (int _i = 0; _i < 2; ++_i) \
;         __builtin_amdgcn_global_load_lds((const unsigned*)((const char*)(gbase) + (voff)[_i]), (PG8_LAS unsigned*)(lds + (bufoff) + ldsw + _i * 8192), 16, 0, 0); } while (0)
; #define PG8_LDA(dst, b, h) do { _Pragma("unroll") for (int m = 0; m < 4; ++m) _Pragma("unroll") for (int k = 0; k < 2; ++k) dst[m][k] = *(const PG8_LAS bf16x8*)(lds + PG8_SA(b, h) + aoff + m * 2048 + k * 1024); } while (0)
; #define PG8_LDB(dst, b, h) do { _Pragma("unroll") for (int n = 0; n < 2; ++n) _Pragma("unroll") for (int k = 0; k < 2; ++k) dst[n][k] = *(const PG8_LAS bf16x8*)(lds + PG8_SB(b, h) + boff + n * 2048 + k * 1024); } while (0)
; #define PG8_MMA(ai, bj, At, Bt) do { __builtin_amdgcn_s_setprio(1); _Pragma("unroll") for (int m = 0; m < 4; ++m) _Pragma("unroll") for (int n = 0; n < 2; ++n) _Pragma("unroll") for (int k = 0; k < 2; ++k) \
;         acc[ai][bj][m][n] = __builtin_amdgcn_mfma_f32_16x16x32_bf16(Bt[n][k], At[m][k], acc[ai][bj][m][n], 0, 0, 0); __builtin_amdgcn_s_setprio(0); } while (0)
; #define PG8_WAIT_V(n) asm volatile("s_waitcnt vmcnt(" #n ")" ::: "memory")
; #define PG8_WAIT_L(n) asm volatile("s_waitcnt lgkmcnt(" #n ")" ::: "memory")
; #define PG8_BAR __builtin_amdgcn_s_barrier()
; #define PG8_SCHED __builtin_amdgcn_sched_barrier(0)
; template <class Epi, class Sched, bool ALIGN_EPI = false, bool SP2 = false>
; __device__ __forceinline__ void gemm_phase(PG8_LAS unsigned char* lds, const Gemm g, const Sched& S, const Epi& E) {
;     ...
;             const bool last = (t == nt - 2);
;             const char* a1 = cA + (size_t)(t + 1) * kstep;
;             const char* a2 = last ? nA : cA + (size_t)(t + 2) * kstep; const char* b2 = last ? nB : cB + (size_t)(t + 2) * kstep;
;             const char* a3 = a2 + kstep; const char* b3 = b2 + kstep;
;             if (last && has_next) S.a_ready(nxt);
;             if constexpr (SP2) {
;             PG8_LDB(B0, 0, 0); PG8_LDB(B1, 0, 1); PG8_SCHED; PG8_LDA(At, 0, 0); PG8_STAGE(PG8_SA(1, 1), a1 + hstepA, voffA);
;             PG8_WAIT_V(8); PG8_WAIT_L(0); PG8_BAR; PG8_MMA(0, 0, At, B0); PG8_MMA(0, 1, At, B1); PG8_BAR; PG8_SCHED;
;             PG8_LDA(At, 0, 1); PG8_STAGE(PG8_SB(0, 0), b2, voffB); PG8_STAGE(PG8_SB(0, 1), b2 + hstepB, voffB); PG8_STAGE(PG8_SA(0, 0), a2, voffA);
.LBB0_171:
	v_add_u32_e32 v76, 0x10000, v162
	v_add_u32_e32 v158, 0x14000, v162
	ds_read_b128 v[64:67], v76
	ds_read_b128 v[68:71], v76 offset:1024
	ds_read_b128 v[72:75], v76 offset:2048
	ds_read_b128 v[76:79], v76 offset:3072
	ds_read_b128 v[154:157], v158
	ds_read_b128 v[164:167], v158 offset:1024
	ds_read_b128 v[168:171], v158 offset:2048
	ds_read_b128 v[172:175], v158 offset:3072
	ds_read_b128 v[176:179], v163
	ds_read_b128 v[180:183], v163 offset:1024
	ds_read_b128 v[184:187], v163 offset:2048
	ds_read_b128 v[194:197], v163 offset:3072
	ds_read_b128 v[230:233], v163 offset:4096
	ds_read_b128 v[234:237], v163 offset:5120
	ds_read_b128 v[238:241], v163 offset:6144
	ds_read_b128 v[242:245], v163 offset:7168
	s_add_u32 s50, s8, 0xfffc0080
	s_addc_u32 s51, s9, -1
	s_add_i32 s60, 0, 0x10000
	s_cmp_eq_u32 s59, 12
	s_cselect_b32 s53, s11, s51
	s_cselect_b32 s52, s37, s50
	s_cselect_b32 s51, s35, s58
	s_cselect_b32 s50, s54, s55
	s_add_i32 s62, 0, 0x14000
	v_lshl_add_u64 v[158:159], s[8:9], 0, v[150:151]
	s_add_i32 m0, s57, 0xc000
	global_load_lds_dwordx4 v[158:159], off
	s_add_i32 m0, s57, 0xe000
	v_lshl_add_u64 v[158:159], s[8:9], 0, v[152:153]
	global_load_lds_dwordx4 v[158:159], off
	s_waitcnt vmcnt(8)
	s_waitcnt lgkmcnt(0)
	s_barrier
	s_setprio 1
	s_waitcnt lgkmcnt(0)
	v_mfma_f32_16x16x32_bf16 v[140:143], v[64:67], v[176:179], v[140:143]
	v_mfma_f32_16x16x32_bf16 v[136:139], v[72:75], v[176:179], v[136:139]
	v_mfma_f32_16x16x32_bf16 v[124:127], v[64:67], v[184:187], v[124:127]
	v_mfma_f32_16x16x32_bf16 v[120:123], v[72:75], v[184:187], v[120:123]
	v_mfma_f32_16x16x32_bf16 v[108:111], v[64:67], v[230:233], v[108:111]
	v_mfma_f32_16x16x32_bf16 v[104:107], v[72:75], v[230:233], v[104:107]
	v_mfma_f32_16x16x32_bf16 v[92:95], v[64:67], v[238:241], v[92:95]
	v_mfma_f32_16x16x32_bf16 v[88:91], v[72:75], v[238:241], v[88:91]
	v_mfma_f32_16x16x32_bf16 v[140:143], v[68:71], v[180:183], v[140:143]
	v_mfma_f32_16x16x32_bf16 v[136:139], v[76:79], v[180:183], v[136:139]
	v_mfma_f32_16x16x32_bf16 v[124:127], v[68:71], v[194:197], v[124:127]
	v_mfma_f32_16x16x32_bf16 v[120:123], v[76:79], v[194:197], v[120:123]
	v_mfma_f32_16x16x32_bf16 v[108:111], v[68:71], v[234:237], v[108:111]
	v_mfma_f32_16x16x32_bf16 v[104:107], v[76:79], v[234:237], v[104:107]
	v_mfma_f32_16x16x32_bf16 v[92:95], v[68:71], v[242:245], v[92:95]
	v_mfma_f32_16x16x32_bf16 v[88:91], v[76:79], v[242:245], v[88:91]
	s_setprio 0
	s_setprio 1
	v_mfma_f32_16x16x32_bf16 v[132:135], v[154:157], v[176:179], v[132:135]
	v_mfma_f32_16x16x32_bf16 v[128:131], v[168:171], v[176:179], v[128:131]
	v_mfma_f32_16x16x32_bf16 v[116:119], v[154:157], v[184:187], v[116:119]
	v_mfma_f32_16x16x32_bf16 v[112:115], v[168:171], v[184:187], v[112:115]
	v_mfma_f32_16x16x32_bf16 v[100:103], v[154:157], v[230:233], v[100:103]
	v_mfma_f32_16x16x32_bf16 v[96:99], v[168:171], v[230:233], v[96:99]
	v_mfma_f32_16x16x32_bf16 v[84:87], v[154:157], v[238:241], v[84:87]
	v_mfma_f32_16x16x32_bf16 v[80:83], v[168:171], v[238:241], v[80:83]
	v_mfma_f32_16x16x32_bf16 v[132:135], v[164:167], v[180:183], v[132:135]
	v_mfma_f32_16x16x32_bf16 v[128:131], v[172:175], v[180:183], v[128:131]
	v_mfma_f32_16x16x32_bf16 v[116:119], v[164:167], v[194:197], v[116:119]
	v_mfma_f32_16x16x32_bf16 v[112:115], v[172:175], v[194:197], v[112:115]
	v_mfma_f32_16x16x32_bf16 v[100:103], v[164:167], v[234:237], v[100:103]
	v_mfma_f32_16x16x32_bf16 v[96:99], v[172:175], v[234:237], v[96:99]
	v_mfma_f32_16x16x32_bf16 v[84:87], v[164:167], v[242:245], v[84:87]
	v_mfma_f32_16x16x32_bf16 v[80:83], v[172:175], v[242:245], v[80:83]
	s_setprio 0
	s_barrier
	ds_read_b128 v[176:179], v163 offset:16384
	ds_read_b128 v[180:183], v163 offset:17408
	ds_read_b128 v[184:187], v163 offset:18432
	ds_read_b128 v[194:197], v163 offset:19456
	ds_read_b128 v[230:233], v163 offset:20480
	ds_read_b128 v[234:237], v163 offset:21504
	ds_read_b128 v[238:241], v163 offset:22528
	ds_read_b128 v[242:245], v163 offset:23552
	s_add_i32 s60, s60, s69
	v_lshl_add_u64 v[158:159], s[50:51], 0, v[188:189]
	s_mov_b32 m0, s60
	global_load_lds_dwordx4 v[158:159], off
	s_add_i32 m0, s60, 0x2000
	s_add_u32 s60, s50, 0x40000
	v_lshl_add_u64 v[246:247], s[50:51], 0, v[148:149]
	s_addc_u32 s61, s51, 0
	s_add_i32 s62, s62, s69
	global_load_lds_dwordx4 v[246:247], off
	v_lshl_add_u64 v[248:249], s[60:61], 0, v[188:189]
	s_mov_b32 m0, s62
	v_lshl_add_u64 v[250:251], s[52:53], 0, v[146:147]
	global_load_lds_dwordx4 v[248:249], off
	s_add_i32 m0, s62, 0x2000
	v_lshl_add_u64 v[248:249], s[60:61], 0, v[148:149]
	global_load_lds_dwordx4 v[248:249], off
	s_mov_b32 m0, s57
	v_lshl_add_u64 v[248:249], s[52:53], 0, v[144:145]
	global_load_lds_dwordx4 v[248:249], off
	s_mov_b32 m0, s78
	s_nop 0
	global_load_lds_dwordx4 v[250:251], off
	s_waitcnt vmcnt(8)
	s_waitcnt lgkmcnt(0)
	s_barrier
; #define PG8_STAGE(bufoff, gbase, voff) do { _Pragma("unroll") for (int _i = 0; _i < 2; ++_i) \
;         __builtin_amdgcn_global_load_lds((const unsigned*)((const char*)(gbase) + (voff)[_i]), (PG8_LAS unsigned*)(lds + (bufoff) + ldsw + _i * 8192), 16, 0, 0); } while (0)
; #define PG8_LDA(dst, b, h) do { _Pragma("unroll") for (int m = 0; m < 4; ++m) _Pragma("unroll") for (int k = 0; k < 2; ++k) dst[m][k] = *(const PG8_LAS bf16x8*)(lds + PG8_SA(b, h) + aoff + m * 2048 + k * 1024); } while (0)
; #define PG8_LDB(dst, b, h) do { _Pragma("unroll") for (int n = 0; n < 2; ++n) _Pragma("unroll") for (int k = 0; k < 2; ++k) dst[n][k] = *(const PG8_LAS bf16x8*)(lds + PG8_SB(b, h) + boff + n * 2048 + k * 1024); } while (0)
; #define PG8_MMA(ai, bj, At, Bt) do { __builtin_amdgcn_s_setprio(1); _Pragma("unroll") for (int m = 0; m < 4; ++m) _Pragma("unroll") for (int n = 0; n < 2; ++n) _Pragma("unroll") for (int k = 0; k < 2; ++k) \
;         acc[ai][bj][m][n] = __builtin_amdgcn_mfma_f32_16x16x32_bf16(Bt[n][k], At[m][k], acc[ai][bj][m][n], 0, 0, 0); __builtin_amdgcn_s_setprio(0); } while (0)
; #define PG8_WAIT_V(n) asm volatile("s_waitcnt vmcnt(" #n ")" ::: "memory")
; #define PG8_WAIT_L(n) asm volatile("s_waitcnt lgkmcnt(" #n ")" ::: "memory")
; #define PG8_BAR __builtin_amdgcn_s_barrier()
; #define PG8_SCHED __builtin_amdgcn_sched_barrier(0)
; template <class Epi, class Sched, bool ALIGN_EPI = false, bool SP2 = false>
; __device__ __forceinline__ void gemm_phase(PG8_LAS unsigned char* lds, const Gemm g, const Sched& S, const Epi& E) {
;     ...
;             PG8_WAIT_V(8); PG8_WAIT_L(0); PG8_BAR; PG8_MMA(1, 0, At, B0); PG8_MMA(1, 1, At, B1); PG8_BAR; PG8_SCHED;
;             PG8_LDB(B0, 1, 0); PG8_LDB(B1, 1, 1); PG8_SCHED; PG8_LDA(At, 1, 0); PG8_STAGE(PG8_SA(0, 1), a2 + hstepA, voffA);
;             PG8_WAIT_V(8); PG8_WAIT_L(0); PG8_BAR; PG8_MMA(0, 0, At, B0); PG8_MMA(0, 1, At, B1); PG8_BAR; PG8_SCHED;
	s_setprio 1
	s_waitcnt lgkmcnt(0)
	v_mfma_f32_16x16x32_bf16 v[60:63], v[64:67], v[176:179], v[60:63]
	v_mfma_f32_16x16x32_bf16 v[56:59], v[72:75], v[176:179], v[56:59]
	v_mfma_f32_16x16x32_bf16 v[44:47], v[64:67], v[184:187], v[44:47]
	v_mfma_f32_16x16x32_bf16 v[40:43], v[72:75], v[184:187], v[40:43]
	v_mfma_f32_16x16x32_bf16 v[28:31], v[64:67], v[230:233], v[28:31]
	v_mfma_f32_16x16x32_bf16 v[24:27], v[72:75], v[230:233], v[24:27]
	v_mfma_f32_16x16x32_bf16 v[12:15], v[64:67], v[238:241], v[12:15]
	v_mfma_f32_16x16x32_bf16 v[8:11], v[72:75], v[238:241], v[8:11]
	v_mfma_f32_16x16x32_bf16 v[60:63], v[68:71], v[180:183], v[60:63]
	v_mfma_f32_16x16x32_bf16 v[56:59], v[76:79], v[180:183], v[56:59]
	v_mfma_f32_16x16x32_bf16 v[44:47], v[68:71], v[194:197], v[44:47]
	v_mfma_f32_16x16x32_bf16 v[40:43], v[76:79], v[194:197], v[40:43]
	v_mfma_f32_16x16x32_bf16 v[28:31], v[68:71], v[234:237], v[28:31]
	v_mfma_f32_16x16x32_bf16 v[24:27], v[76:79], v[234:237], v[24:27]
	v_mfma_f32_16x16x32_bf16 v[12:15], v[68:71], v[242:245], v[12:15]
	v_mfma_f32_16x16x32_bf16 v[8:11], v[76:79], v[242:245], v[8:11]
	s_setprio 0
	s_setprio 1
	v_mfma_f32_16x16x32_bf16 v[52:55], v[154:157], v[176:179], v[52:55]
	v_mfma_f32_16x16x32_bf16 v[48:51], v[168:171], v[176:179], v[48:51]
	v_mfma_f32_16x16x32_bf16 v[36:39], v[154:157], v[184:187], v[36:39]
	v_mfma_f32_16x16x32_bf16 v[32:35], v[168:171], v[184:187], v[32:35]
	v_mfma_f32_16x16x32_bf16 v[20:23], v[154:157], v[230:233], v[20:23]
	v_mfma_f32_16x16x32_bf16 v[16:19], v[168:171], v[230:233], v[16:19]
	v_mfma_f32_16x16x32_bf16 v[4:7], v[154:157], v[238:241], v[4:7]
	v_mfma_f32_16x16x32_bf16 v[0:3], v[168:171], v[238:241], v[0:3]
	v_mfma_f32_16x16x32_bf16 v[52:55], v[164:167], v[180:183], v[52:55]
	v_mfma_f32_16x16x32_bf16 v[48:51], v[172:175], v[180:183], v[48:51]
	v_mfma_f32_16x16x32_bf16 v[36:39], v[164:167], v[194:197], v[36:39]
	v_mfma_f32_16x16x32_bf16 v[32:35], v[172:175], v[194:197], v[32:35]
	v_mfma_f32_16x16x32_bf16 v[20:23], v[164:167], v[234:237], v[20:23]
	v_mfma_f32_16x16x32_bf16 v[16:19], v[172:175], v[234:237], v[16:19]
	v_mfma_f32_16x16x32_bf16 v[4:7], v[164:167], v[242:245], v[4:7]
	v_mfma_f32_16x16x32_bf16 v[0:3], v[172:175], v[242:245], v[0:3]
	s_setprio 0
	s_barrier
	v_add_u32_e32 v76, 0x18000, v162
	v_add_u32_e32 v172, 0x1c000, v162
	ds_read_b128 v[64:67], v76
	ds_read_b128 v[68:71], v76 offset:1024
	ds_read_b128 v[72:75], v76 offset:2048
	ds_read_b128 v[76:79], v76 offset:3072
	ds_read_b128 v[154:157], v172
	ds_read_b128 v[164:167], v172 offset:1024
	ds_read_b128 v[168:171], v172 offset:2048
	ds_read_b128 v[172:175], v172 offset:3072
	ds_read_b128 v[176:179], v163 offset:32768
	ds_read_b128 v[180:183], v163 offset:33792
	ds_read_b128 v[184:187], v163 offset:34816
	ds_read_b128 v[194:197], v163 offset:35840
	ds_read_b128 v[230:233], v163 offset:36864
	ds_read_b128 v[234:237], v163 offset:37888
	ds_read_b128 v[238:241], v163 offset:38912
	ds_read_b128 v[242:245], v163 offset:39936
	s_add_i32 s60, 0, 0x18000
	s_add_i32 s61, 0, 0x1c000
	s_add_u32 s52, s52, 0x40000
	s_addc_u32 s53, s53, 0
	s_mov_b32 m0, s81
	v_lshl_add_u64 v[252:253], s[52:53], 0, v[144:145]
	global_load_lds_dwordx4 v[252:253], off
	s_mov_b32 m0, s80
	v_lshl_add_u64 v[252:253], s[52:53], 0, v[146:147]
	global_load_lds_dwordx4 v[252:253], off
	s_waitcnt vmcnt(8)
	s_waitcnt lgkmcnt(0)
	s_barrier
	s_setprio 1
	s_waitcnt lgkmcnt(0)
	v_mfma_f32_16x16x32_bf16 v[140:143], v[64:67], v[176:179], v[140:143]
	v_mfma_f32_16x16x32_bf16 v[136:139], v[72:75], v[176:179], v[136:139]
	v_mfma_f32_16x16x32_bf16 v[124:127], v[64:67], v[184:187], v[124:127]
	v_mfma_f32_16x16x32_bf16 v[120:123], v[72:75], v[184:187], v[120:123]
	v_mfma_f32_16x16x32_bf16 v[108:111], v[64:67], v[230:233], v[108:111]
	v_mfma_f32_16x16x32_bf16 v[104:107], v[72:75], v[230:233], v[104:107]
	v_mfma_f32_16x16x32_bf16 v[92:95], v[64:67], v[238:241], v[92:95]
	v_mfma_f32_16x16x32_bf16 v[88:91], v[72:75], v[238:241], v[88:91]
	v_mfma_f32_16x16x32_bf16 v[140:143], v[68:71], v[180:183], v[140:143]
	v_mfma_f32_16x16x32_bf16 v[136:139], v[76:79], v[180:183], v[136:139]
	v_mfma_f32_16x16x32_bf16 v[124:127], v[68:71], v[194:197], v[124:127]
	v_mfma_f32_16x16x32_bf16 v[120:123], v[76:79], v[194:197], v[120:123]
	v_mfma_f32_16x16x32_bf16 v[108:111], v[68:71], v[234:237], v[108:111]
	v_mfma_f32_16x16x32_bf16 v[104:107], v[76:79], v[234:237], v[104:107]
	v_mfma_f32_16x16x32_bf16 v[92:95], v[68:71], v[242:245], v[92:95]
	v_mfma_f32_16x16x32_bf16 v[88:91], v[76:79], v[242:245], v[88:91]
	s_setprio 0
	s_setprio 1
	v_mfma_f32_16x16x32_bf16 v[132:135], v[154:157], v[176:179], v[132:135]
	v_mfma_f32_16x16x32_bf16 v[128:131], v[168:171], v[176:179], v[128:131]
	v_mfma_f32_16x16x32_bf16 v[116:119], v[154:157], v[184:187], v[116:119]
	v_mfma_f32_16x16x32_bf16 v[112:115], v[168:171], v[184:187], v[112:115]
	v_mfma_f32_16x16x32_bf16 v[100:103], v[154:157], v[230:233], v[100:103]
	v_mfma_f32_16x16x32_bf16 v[96:99], v[168:171], v[230:233], v[96:99]
	v_mfma_f32_16x16x32_bf16 v[84:87], v[154:157], v[238:241], v[84:87]
	v_mfma_f32_16x16x32_bf16 v[80:83], v[168:171], v[238:241], v[80:83]
	v_mfma_f32_16x16x32_bf16 v[132:135], v[164:167], v[180:183], v[132:135]
	v_mfma_f32_16x16x32_bf16 v[128:131], v[172:175], v[180:183], v[128:131]
	v_mfma_f32_16x16x32_bf16 v[116:119], v[164:167], v[194:197], v[116:119]
	v_mfma_f32_16x16x32_bf16 v[112:115], v[172:175], v[194:197], v[112:115]
	v_mfma_f32_16x16x32_bf16 v[100:103], v[164:167], v[234:237], v[100:103]
	v_mfma_f32_16x16x32_bf16 v[96:99], v[172:175], v[234:237], v[96:99]
	v_mfma_f32_16x16x32_bf16 v[84:87], v[164:167], v[242:245], v[84:87]
	v_mfma_f32_16x16x32_bf16 v[80:83], v[172:175], v[242:245], v[80:83]
	s_setprio 0
	s_barrier
; #define PG8_STAGE(bufoff, gbase, voff) do { _Pragma("unroll") for (int _i = 0; _i < 2; ++_i) \
;         __builtin_amdgcn_global_load_lds((const unsigned*)((const char*)(gbase) + (voff)[_i]), (PG8_LAS unsigned*)(lds + (bufoff) + ldsw + _i * 8192), 16, 0, 0); } while (0)
; #define PG8_LDA(dst, b, h) do { _Pragma("unroll") for (int m = 0; m < 4; ++m) _Pragma("unroll") for (int k = 0; k < 2; ++k) dst[m][k] = *(const PG8_LAS bf16x8*)(lds + PG8_SA(b, h) + aoff + m * 2048 + k * 1024); } while (0)
; #define PG8_MMA(ai, bj, At, Bt) do { __builtin_amdgcn_s_setprio(1); _Pragma("unroll") for (int m = 0; m < 4; ++m) _Pragma("unroll") for (int n = 0; n < 2; ++n) _Pragma("unroll") for (int k = 0; k < 2; ++k) \
;         acc[ai][bj][m][n] = __builtin_amdgcn_mfma_f32_16x16x32_bf16(Bt[n][k], At[m][k], acc[ai][bj][m][n], 0, 0, 0); __builtin_amdgcn_s_setprio(0); } while (0)
; #define PG8_WAIT_V(n) asm volatile("s_waitcnt vmcnt(" #n ")" ::: "memory")
; #define PG8_WAIT_L(n) asm volatile("s_waitcnt lgkmcnt(" #n ")" ::: "memory")
; #define PG8_BAR __builtin_amdgcn_s_barrier()
; #define PG8_SCHED __builtin_amdgcn_sched_barrier(0)
; template <class Epi, class Sched, bool ALIGN_EPI = false, bool SP2 = false>
; __device__ __forceinline__ void gemm_phase(PG8_LAS unsigned char* lds, const Gemm g, const Sched& S, const Epi& E) {
;     ...
;         for (int t = 0; t < nt; t += 2) {
;     ...
;             PG8_LDA(At, 1, 1); PG8_STAGE(PG8_SB(1, 0), b3, voffB); PG8_STAGE(PG8_SB(1, 1), b3 + hstepB, voffB); PG8_STAGE(PG8_SA(1, 0), a3, voffA);
;             PG8_WAIT_V(8); PG8_WAIT_L(0); PG8_BAR; PG8_MMA(1, 0, At, B0); PG8_MMA(1, 1, At, B1); PG8_BAR; PG8_SCHED;
	ds_read_b128 v[176:179], v163 offset:49152
	ds_read_b128 v[180:183], v163 offset:50176
	ds_read_b128 v[184:187], v163 offset:51200
	ds_read_b128 v[194:197], v163 offset:52224
	ds_read_b128 v[230:233], v163 offset:53248
	ds_read_b128 v[234:237], v163 offset:54272
	ds_read_b128 v[238:241], v163 offset:55296
	ds_read_b128 v[242:245], v163 offset:56320
	s_add_i32 s52, s60, s69
	v_lshl_add_u64 v[158:159], v[158:159], 0, s[94:95]
	s_mov_b32 m0, s52
	global_load_lds_dwordx4 v[158:159], off
	s_add_i32 m0, s52, 0x2000
	s_add_u32 s50, s50, 0x40080
	v_lshl_add_u64 v[158:159], v[246:247], 0, s[94:95]
	s_addc_u32 s51, s51, 0
	s_add_i32 s52, s61, s69
	global_load_lds_dwordx4 v[158:159], off
	s_mov_b32 m0, s52
	v_lshl_add_u64 v[158:159], s[50:51], 0, v[188:189]
	global_load_lds_dwordx4 v[158:159], off
	s_add_i32 m0, s52, 0x2000
	v_lshl_add_u64 v[158:159], s[50:51], 0, v[148:149]
	global_load_lds_dwordx4 v[158:159], off
	s_mov_b32 m0, s2
	v_lshl_add_u64 v[158:159], v[248:249], 0, s[94:95]
	global_load_lds_dwordx4 v[158:159], off
	s_mov_b32 m0, s4
	v_lshl_add_u64 v[158:159], v[250:251], 0, s[94:95]
	global_load_lds_dwordx4 v[158:159], off
	s_waitcnt vmcnt(8)
	s_waitcnt lgkmcnt(0)
	s_barrier
	s_setprio 1
	s_waitcnt lgkmcnt(0)
	v_mfma_f32_16x16x32_bf16 v[60:63], v[64:67], v[176:179], v[60:63]
	v_mfma_f32_16x16x32_bf16 v[56:59], v[72:75], v[176:179], v[56:59]
	v_mfma_f32_16x16x32_bf16 v[44:47], v[64:67], v[184:187], v[44:47]
	v_mfma_f32_16x16x32_bf16 v[40:43], v[72:75], v[184:187], v[40:43]
	v_mfma_f32_16x16x32_bf16 v[28:31], v[64:67], v[230:233], v[28:31]
	v_mfma_f32_16x16x32_bf16 v[24:27], v[72:75], v[230:233], v[24:27]
	v_mfma_f32_16x16x32_bf16 v[12:15], v[64:67], v[238:241], v[12:15]
	v_mfma_f32_16x16x32_bf16 v[8:11], v[72:75], v[238:241], v[8:11]
	v_mfma_f32_16x16x32_bf16 v[60:63], v[68:71], v[180:183], v[60:63]
	v_mfma_f32_16x16x32_bf16 v[56:59], v[76:79], v[180:183], v[56:59]
	v_mfma_f32_16x16x32_bf16 v[44:47], v[68:71], v[194:197], v[44:47]
	v_mfma_f32_16x16x32_bf16 v[40:43], v[76:79], v[194:197], v[40:43]
	v_mfma_f32_16x16x32_bf16 v[28:31], v[68:71], v[234:237], v[28:31]
	v_mfma_f32_16x16x32_bf16 v[24:27], v[76:79], v[234:237], v[24:27]
	v_mfma_f32_16x16x32_bf16 v[12:15], v[68:71], v[242:245], v[12:15]
	v_mfma_f32_16x16x32_bf16 v[8:11], v[76:79], v[242:245], v[8:11]
	s_setprio 0
	s_setprio 1
	v_mfma_f32_16x16x32_bf16 v[52:55], v[154:157], v[176:179], v[52:55]
	v_mfma_f32_16x16x32_bf16 v[48:51], v[168:171], v[176:179], v[48:51]
	v_mfma_f32_16x16x32_bf16 v[36:39], v[154:157], v[184:187], v[36:39]
	v_mfma_f32_16x16x32_bf16 v[32:35], v[168:171], v[184:187], v[32:35]
	v_mfma_f32_16x16x32_bf16 v[20:23], v[154:157], v[230:233], v[20:23]
	v_mfma_f32_16x16x32_bf16 v[16:19], v[168:171], v[230:233], v[16:19]
	v_mfma_f32_16x16x32_bf16 v[4:7], v[154:157], v[238:241], v[4:7]
	v_mfma_f32_16x16x32_bf16 v[0:3], v[168:171], v[238:241], v[0:3]
	v_mfma_f32_16x16x32_bf16 v[52:55], v[164:167], v[180:183], v[52:55]
	v_mfma_f32_16x16x32_bf16 v[48:51], v[172:175], v[180:183], v[48:51]
	v_mfma_f32_16x16x32_bf16 v[36:39], v[164:167], v[194:197], v[36:39]
	v_mfma_f32_16x16x32_bf16 v[32:35], v[172:175], v[194:197], v[32:35]
	v_mfma_f32_16x16x32_bf16 v[20:23], v[164:167], v[234:237], v[20:23]
	v_mfma_f32_16x16x32_bf16 v[16:19], v[172:175], v[234:237], v[16:19]
	v_mfma_f32_16x16x32_bf16 v[4:7], v[164:167], v[242:245], v[4:7]
	v_mfma_f32_16x16x32_bf16 v[0:3], v[172:175], v[242:245], v[0:3]
	s_setprio 0
	s_barrier
	s_add_i32 s59, s59, 2
	s_add_u32 s8, s8, 0x100
	s_addc_u32 s9, s9, 0
	s_add_u32 s55, s55, 0x100
	s_addc_u32 s58, s58, 0
	s_cmp_gt_u32 s59, 13
	s_cbranch_scc0 .LBB0_171
	s_and_b64 vcc, exec, s[30:31]
	s_cbranch_vccz .LBB0_174
	s_barrier

; #define PG8_STAGE(bufoff, gbase, voff) do { _Pragma("unroll") for (int _i = 0; _i < 2; ++_i) \
;         __builtin_amdgcn_global_load_lds((const unsigned*)((const char*)(gbase) + (voff)[_i]), (PG8_LAS unsigned*)(lds + (bufoff) + ldsw + _i * 8192), 16, 0, 0); } while (0)
; #define PG8_LDA(dst, b, h) do { _Pragma("unroll") for (int m = 0; m < 4; ++m) _Pragma("unroll") for (int k = 0; k < 2; ++k) dst[m][k] = *(const PG8_LAS bf16x8*)(lds + PG8_SA(b, h) + aoff + m * 2048 + k * 1024); } while (0)
; #define PG8_LDB(dst, b, h) do { _Pragma("unroll") for (int n = 0; n < 2; ++n) _Pragma("unroll") for (int k = 0; k < 2; ++k) dst[n][k] = *(const PG8_LAS bf16x8*)(lds + PG8_SB(b, h) + boff + n * 2048 + k * 1024); } while (0)
; #define PG8_MMA(ai, bj, At, Bt) do { __builtin_amdgcn_s_setprio(1); _Pragma("unroll") for (int m = 0; m < 4; ++m) _Pragma("unroll") for (int n = 0; n < 2; ++n) _Pragma("unroll") for (int k = 0; k < 2; ++k) \
;         acc[ai][bj][m][n] = __builtin_amdgcn_mfma_f32_16x16x32_bf16(Bt[n][k], At[m][k], acc[ai][bj][m][n], 0, 0, 0); __builtin_amdgcn_s_setprio(0); } while (0)
; #define PG8_WAIT_V(n) asm volatile("s_waitcnt vmcnt(" #n ")" ::: "memory")
; #define PG8_WAIT_L(n) asm volatile("s_waitcnt lgkmcnt(" #n ")" ::: "memory")
; #define PG8_BAR __builtin_amdgcn_s_barrier()
; #define PG8_SCHED __builtin_amdgcn_sched_barrier(0)
; template <class Epi, class Sched, bool ALIGN_EPI = false, bool SP2 = false>
; __device__ __forceinline__ void gemm_phase(PG8_LAS unsigned char* lds, const Gemm g, const Sched& S, const Epi& E) {
;     ...
;             const bool last = (t == nt - 2);
;             const char* a1 = cA + (size_t)(t + 1) * kstep;
;             const char* a2 = last ? nA : cA + (size_t)(t + 2) * kstep; const char* b2 = last ? nB : cB + (size_t)(t + 2) * kstep;
;             const char* a3 = a2 + kstep; const char* b3 = b2 + kstep;
;             if (last && has_next) S.a_ready(nxt);
;             if constexpr (SP2) {
;             PG8_LDB(B0, 0, 0); PG8_LDB(B1, 0, 1); PG8_SCHED; PG8_LDA(At, 0, 0); PG8_STAGE(PG8_SA(1, 1), a1 + hstepA, voffA);
;             PG8_WAIT_V(8); PG8_WAIT_L(0); PG8_BAR; PG8_MMA(0, 0, At, B0); PG8_MMA(0, 1, At, B1); PG8_BAR; PG8_SCHED;
;             PG8_LDA(At, 0, 1); PG8_STAGE(PG8_SB(0, 0), b2, voffB); PG8_STAGE(PG8_SB(0, 1), b2 + hstepB, voffB); PG8_STAGE(PG8_SA(0, 0), a2, voffA);
.LBB0_712:
	v_add_u32_e32 v154, 0x10000, v144
	v_add_u32_e32 v170, 0x14000, v144
	ds_read_b128 v[138:141], v154
	ds_read_b128 v[146:149], v154 offset:1024
	ds_read_b128 v[150:153], v154 offset:2048
	ds_read_b128 v[154:157], v154 offset:3072
	ds_read_b128 v[158:161], v170
	ds_read_b128 v[162:165], v170 offset:1024
	ds_read_b128 v[166:169], v170 offset:2048
	ds_read_b128 v[170:173], v170 offset:3072
	ds_read_b128 v[174:177], v145
	ds_read_b128 v[178:181], v145 offset:1024
	ds_read_b128 v[182:185], v145 offset:2048
	ds_read_b128 v[192:195], v145 offset:3072
	ds_read_b128 v[230:233], v145 offset:4096
	ds_read_b128 v[234:237], v145 offset:5120
	ds_read_b128 v[238:241], v145 offset:6144
	ds_read_b128 v[242:245], v145 offset:7168
	s_add_u32 s28, s26, 0xfffc0080
	s_addc_u32 s29, s27, -1
	s_add_i32 s33, 0, 0x10000
	s_cmp_eq_u32 s19, 12
	s_cselect_b32 s31, s1, s29
	s_cselect_b32 s30, s2, s28
	s_cselect_b32 s29, s3, s17
	s_cselect_b32 s28, s4, s9
	s_add_i32 s51, 0, 0x14000
	v_lshl_add_u64 v[186:187], s[26:27], 0, v[134:135]
	s_add_i32 m0, s25, 0xc000
	global_load_lds_dwordx4 v[186:187], off
	s_add_i32 m0, s25, 0xe000
	v_lshl_add_u64 v[186:187], s[26:27], 0, v[136:137]
	global_load_lds_dwordx4 v[186:187], off
	s_waitcnt vmcnt(8)
	s_waitcnt lgkmcnt(0)
	s_barrier
	s_setprio 1
	s_waitcnt lgkmcnt(0)
	v_mfma_f32_16x16x32_bf16 v[124:127], v[138:141], v[174:177], v[124:127]
	v_mfma_f32_16x16x32_bf16 v[120:123], v[150:153], v[174:177], v[120:123]
	v_mfma_f32_16x16x32_bf16 v[108:111], v[138:141], v[182:185], v[108:111]
	v_mfma_f32_16x16x32_bf16 v[104:107], v[150:153], v[182:185], v[104:107]
	v_mfma_f32_16x16x32_bf16 v[92:95], v[138:141], v[230:233], v[92:95]
	v_mfma_f32_16x16x32_bf16 v[88:91], v[150:153], v[230:233], v[88:91]
	v_mfma_f32_16x16x32_bf16 v[76:79], v[138:141], v[238:241], v[76:79]
	v_mfma_f32_16x16x32_bf16 v[72:75], v[150:153], v[238:241], v[72:75]
	v_mfma_f32_16x16x32_bf16 v[124:127], v[146:149], v[178:181], v[124:127]
	v_mfma_f32_16x16x32_bf16 v[120:123], v[154:157], v[178:181], v[120:123]
	v_mfma_f32_16x16x32_bf16 v[108:111], v[146:149], v[192:195], v[108:111]
	v_mfma_f32_16x16x32_bf16 v[104:107], v[154:157], v[192:195], v[104:107]
	v_mfma_f32_16x16x32_bf16 v[92:95], v[146:149], v[234:237], v[92:95]
	v_mfma_f32_16x16x32_bf16 v[88:91], v[154:157], v[234:237], v[88:91]
	v_mfma_f32_16x16x32_bf16 v[76:79], v[146:149], v[242:245], v[76:79]
	v_mfma_f32_16x16x32_bf16 v[72:75], v[154:157], v[242:245], v[72:75]
	s_setprio 0
	s_setprio 1
	v_mfma_f32_16x16x32_bf16 v[116:119], v[158:161], v[174:177], v[116:119]
	v_mfma_f32_16x16x32_bf16 v[112:115], v[166:169], v[174:177], v[112:115]
	v_mfma_f32_16x16x32_bf16 v[100:103], v[158:161], v[182:185], v[100:103]
	v_mfma_f32_16x16x32_bf16 v[96:99], v[166:169], v[182:185], v[96:99]
	v_mfma_f32_16x16x32_bf16 v[84:87], v[158:161], v[230:233], v[84:87]
	v_mfma_f32_16x16x32_bf16 v[80:83], v[166:169], v[230:233], v[80:83]
	v_mfma_f32_16x16x32_bf16 v[68:71], v[158:161], v[238:241], v[68:71]
	v_mfma_f32_16x16x32_bf16 v[64:67], v[166:169], v[238:241], v[64:67]
	v_mfma_f32_16x16x32_bf16 v[116:119], v[162:165], v[178:181], v[116:119]
	v_mfma_f32_16x16x32_bf16 v[112:115], v[170:173], v[178:181], v[112:115]
	v_mfma_f32_16x16x32_bf16 v[100:103], v[162:165], v[192:195], v[100:103]
	v_mfma_f32_16x16x32_bf16 v[96:99], v[170:173], v[192:195], v[96:99]
	v_mfma_f32_16x16x32_bf16 v[84:87], v[162:165], v[234:237], v[84:87]
	v_mfma_f32_16x16x32_bf16 v[80:83], v[170:173], v[234:237], v[80:83]
	v_mfma_f32_16x16x32_bf16 v[68:71], v[162:165], v[242:245], v[68:71]
	v_mfma_f32_16x16x32_bf16 v[64:67], v[170:173], v[242:245], v[64:67]
	s_setprio 0
	s_barrier
	ds_read_b128 v[174:177], v145 offset:16384
	ds_read_b128 v[178:181], v145 offset:17408
	ds_read_b128 v[182:185], v145 offset:18432
	ds_read_b128 v[192:195], v145 offset:19456
	ds_read_b128 v[230:233], v145 offset:20480
	ds_read_b128 v[234:237], v145 offset:21504
	ds_read_b128 v[238:241], v145 offset:22528
	ds_read_b128 v[242:245], v145 offset:23552
	s_add_i32 s33, s33, s39
	v_lshl_add_u64 v[186:187], s[28:29], 0, v[188:189]
	s_mov_b32 m0, s33
	global_load_lds_dwordx4 v[186:187], off
	s_add_i32 m0, s33, 0x2000
	s_add_u32 s52, s28, 0x40000
	v_lshl_add_u64 v[196:197], s[28:29], 0, v[132:133]
	s_addc_u32 s53, s29, 0
	s_add_i32 s33, s51, s39
	global_load_lds_dwordx4 v[196:197], off
	v_lshl_add_u64 v[246:247], s[52:53], 0, v[188:189]
	s_mov_b32 m0, s33
	v_lshl_add_u64 v[248:249], s[30:31], 0, v[130:131]
	global_load_lds_dwordx4 v[246:247], off
	s_add_i32 m0, s33, 0x2000
	v_lshl_add_u64 v[246:247], s[52:53], 0, v[132:133]
	global_load_lds_dwordx4 v[246:247], off
	s_mov_b32 m0, s25
	v_lshl_add_u64 v[246:247], s[30:31], 0, v[128:129]
	global_load_lds_dwordx4 v[246:247], off
	s_mov_b32 m0, s40
	s_nop 0
	global_load_lds_dwordx4 v[248:249], off
	s_waitcnt vmcnt(8)
	s_waitcnt lgkmcnt(0)
	s_barrier
; #define PG8_STAGE(bufoff, gbase, voff) do { _Pragma("unroll") for (int _i = 0; _i < 2; ++_i) \
;         __builtin_amdgcn_global_load_lds((const unsigned*)((const char*)(gbase) + (voff)[_i]), (PG8_LAS unsigned*)(lds + (bufoff) + ldsw + _i * 8192), 16, 0, 0); } while (0)
; #define PG8_LDA(dst, b, h) do { _Pragma("unroll") for (int m = 0; m < 4; ++m) _Pragma("unroll") for (int k = 0; k < 2; ++k) dst[m][k] = *(const PG8_LAS bf16x8*)(lds + PG8_SA(b, h) + aoff + m * 2048 + k * 1024); } while (0)
; #define PG8_LDB(dst, b, h) do { _Pragma("unroll") for (int n = 0; n < 2; ++n) _Pragma("unroll") for (int k = 0; k < 2; ++k) dst[n][k] = *(const PG8_LAS bf16x8*)(lds + PG8_SB(b, h) + boff + n * 2048 + k * 1024); } while (0)
; #define PG8_MMA(ai, bj, At, Bt) do { __builtin_amdgcn_s_setprio(1); _Pragma("unroll") for (int m = 0; m < 4; ++m) _Pragma("unroll") for (int n = 0; n < 2; ++n) _Pragma("unroll") for (int k = 0; k < 2; ++k) \
;         acc[ai][bj][m][n] = __builtin_amdgcn_mfma_f32_16x16x32_bf16(Bt[n][k], At[m][k], acc[ai][bj][m][n], 0, 0, 0); __builtin_amdgcn_s_setprio(0); } while (0)
; #define PG8_WAIT_V(n) asm volatile("s_waitcnt vmcnt(" #n ")" ::: "memory")
; #define PG8_WAIT_L(n) asm volatile("s_waitcnt lgkmcnt(" #n ")" ::: "memory")
; #define PG8_BAR __builtin_amdgcn_s_barrier()
; #define PG8_SCHED __builtin_amdgcn_sched_barrier(0)
; template <class Epi, class Sched, bool ALIGN_EPI = false, bool SP2 = false>
; __device__ __forceinline__ void gemm_phase(PG8_LAS unsigned char* lds, const Gemm g, const Sched& S, const Epi& E) {
;     ...
;             PG8_WAIT_V(8); PG8_WAIT_L(0); PG8_BAR; PG8_MMA(1, 0, At, B0); PG8_MMA(1, 1, At, B1); PG8_BAR; PG8_SCHED;
;             PG8_LDB(B0, 1, 0); PG8_LDB(B1, 1, 1); PG8_SCHED; PG8_LDA(At, 1, 0); PG8_STAGE(PG8_SA(0, 1), a2 + hstepA, voffA);
;             PG8_WAIT_V(8); PG8_WAIT_L(0); PG8_BAR; PG8_MMA(0, 0, At, B0); PG8_MMA(0, 1, At, B1); PG8_BAR; PG8_SCHED;
	s_setprio 1
	s_waitcnt lgkmcnt(0)
	v_mfma_f32_16x16x32_bf16 v[60:63], v[138:141], v[174:177], v[60:63]
	v_mfma_f32_16x16x32_bf16 v[56:59], v[150:153], v[174:177], v[56:59]
	v_mfma_f32_16x16x32_bf16 v[44:47], v[138:141], v[182:185], v[44:47]
	v_mfma_f32_16x16x32_bf16 v[40:43], v[150:153], v[182:185], v[40:43]
	v_mfma_f32_16x16x32_bf16 v[28:31], v[138:141], v[230:233], v[28:31]
	v_mfma_f32_16x16x32_bf16 v[24:27], v[150:153], v[230:233], v[24:27]
	v_mfma_f32_16x16x32_bf16 v[12:15], v[138:141], v[238:241], v[12:15]
	v_mfma_f32_16x16x32_bf16 v[8:11], v[150:153], v[238:241], v[8:11]
	v_mfma_f32_16x16x32_bf16 v[60:63], v[146:149], v[178:181], v[60:63]
	v_mfma_f32_16x16x32_bf16 v[56:59], v[154:157], v[178:181], v[56:59]
	v_mfma_f32_16x16x32_bf16 v[44:47], v[146:149], v[192:195], v[44:47]
	v_mfma_f32_16x16x32_bf16 v[40:43], v[154:157], v[192:195], v[40:43]
	v_mfma_f32_16x16x32_bf16 v[28:31], v[146:149], v[234:237], v[28:31]
	v_mfma_f32_16x16x32_bf16 v[24:27], v[154:157], v[234:237], v[24:27]
	v_mfma_f32_16x16x32_bf16 v[12:15], v[146:149], v[242:245], v[12:15]
	v_mfma_f32_16x16x32_bf16 v[8:11], v[154:157], v[242:245], v[8:11]
	s_setprio 0
	s_setprio 1
	v_mfma_f32_16x16x32_bf16 v[52:55], v[158:161], v[174:177], v[52:55]
	v_mfma_f32_16x16x32_bf16 v[48:51], v[166:169], v[174:177], v[48:51]
	v_mfma_f32_16x16x32_bf16 v[36:39], v[158:161], v[182:185], v[36:39]
	v_mfma_f32_16x16x32_bf16 v[32:35], v[166:169], v[182:185], v[32:35]
	v_mfma_f32_16x16x32_bf16 v[20:23], v[158:161], v[230:233], v[20:23]
	v_mfma_f32_16x16x32_bf16 v[16:19], v[166:169], v[230:233], v[16:19]
	v_mfma_f32_16x16x32_bf16 v[4:7], v[158:161], v[238:241], v[4:7]
	v_mfma_f32_16x16x32_bf16 v[0:3], v[166:169], v[238:241], v[0:3]
	v_mfma_f32_16x16x32_bf16 v[52:55], v[162:165], v[178:181], v[52:55]
	v_mfma_f32_16x16x32_bf16 v[48:51], v[170:173], v[178:181], v[48:51]
	v_mfma_f32_16x16x32_bf16 v[36:39], v[162:165], v[192:195], v[36:39]
	v_mfma_f32_16x16x32_bf16 v[32:35], v[170:173], v[192:195], v[32:35]
	v_mfma_f32_16x16x32_bf16 v[20:23], v[162:165], v[234:237], v[20:23]
	v_mfma_f32_16x16x32_bf16 v[16:19], v[170:173], v[234:237], v[16:19]
	v_mfma_f32_16x16x32_bf16 v[4:7], v[162:165], v[242:245], v[4:7]
	v_mfma_f32_16x16x32_bf16 v[0:3], v[170:173], v[242:245], v[0:3]
	s_setprio 0
	s_barrier
	v_add_u32_e32 v154, 0x18000, v144
	v_add_u32_e32 v170, 0x1c000, v144
	ds_read_b128 v[138:141], v154
	ds_read_b128 v[146:149], v154 offset:1024
	ds_read_b128 v[150:153], v154 offset:2048
	ds_read_b128 v[154:157], v154 offset:3072
	ds_read_b128 v[158:161], v170
	ds_read_b128 v[162:165], v170 offset:1024
	ds_read_b128 v[166:169], v170 offset:2048
	ds_read_b128 v[170:173], v170 offset:3072
	ds_read_b128 v[174:177], v145 offset:32768
	ds_read_b128 v[178:181], v145 offset:33792
	ds_read_b128 v[182:185], v145 offset:34816
	ds_read_b128 v[192:195], v145 offset:35840
	ds_read_b128 v[230:233], v145 offset:36864
	ds_read_b128 v[234:237], v145 offset:37888
	ds_read_b128 v[238:241], v145 offset:38912
	ds_read_b128 v[242:245], v145 offset:39936
	s_add_i32 s33, 0, 0x18000
	s_add_i32 s51, 0, 0x1c000
	s_add_u32 s30, s30, 0x40000
	s_addc_u32 s31, s31, 0
	s_mov_b32 m0, s41
	v_lshl_add_u64 v[250:251], s[30:31], 0, v[128:129]
	global_load_lds_dwordx4 v[250:251], off
	s_mov_b32 m0, s42
	v_lshl_add_u64 v[250:251], s[30:31], 0, v[130:131]
	global_load_lds_dwordx4 v[250:251], off
	s_waitcnt vmcnt(8)
	s_waitcnt lgkmcnt(0)
	s_barrier
	s_setprio 1
	s_waitcnt lgkmcnt(0)
	v_mfma_f32_16x16x32_bf16 v[124:127], v[138:141], v[174:177], v[124:127]
	v_mfma_f32_16x16x32_bf16 v[120:123], v[150:153], v[174:177], v[120:123]
	v_mfma_f32_16x16x32_bf16 v[108:111], v[138:141], v[182:185], v[108:111]
	v_mfma_f32_16x16x32_bf16 v[104:107], v[150:153], v[182:185], v[104:107]
	v_mfma_f32_16x16x32_bf16 v[92:95], v[138:141], v[230:233], v[92:95]
	v_mfma_f32_16x16x32_bf16 v[88:91], v[150:153], v[230:233], v[88:91]
	v_mfma_f32_16x16x32_bf16 v[76:79], v[138:141], v[238:241], v[76:79]
	v_mfma_f32_16x16x32_bf16 v[72:75], v[150:153], v[238:241], v[72:75]
	v_mfma_f32_16x16x32_bf16 v[124:127], v[146:149], v[178:181], v[124:127]
	v_mfma_f32_16x16x32_bf16 v[120:123], v[154:157], v[178:181], v[120:123]
	v_mfma_f32_16x16x32_bf16 v[108:111], v[146:149], v[192:195], v[108:111]
	v_mfma_f32_16x16x32_bf16 v[104:107], v[154:157], v[192:195], v[104:107]
	v_mfma_f32_16x16x32_bf16 v[92:95], v[146:149], v[234:237], v[92:95]
	v_mfma_f32_16x16x32_bf16 v[88:91], v[154:157], v[234:237], v[88:91]
	v_mfma_f32_16x16x32_bf16 v[76:79], v[146:149], v[242:245], v[76:79]
	v_mfma_f32_16x16x32_bf16 v[72:75], v[154:157], v[242:245], v[72:75]
	s_setprio 0
	s_setprio 1
	v_mfma_f32_16x16x32_bf16 v[116:119], v[158:161], v[174:177], v[116:119]
	v_mfma_f32_16x16x32_bf16 v[112:115], v[166:169], v[174:177], v[112:115]
	v_mfma_f32_16x16x32_bf16 v[100:103], v[158:161], v[182:185], v[100:103]
	v_mfma_f32_16x16x32_bf16 v[96:99], v[166:169], v[182:185], v[96:99]
	v_mfma_f32_16x16x32_bf16 v[84:87], v[158:161], v[230:233], v[84:87]
	v_mfma_f32_16x16x32_bf16 v[80:83], v[166:169], v[230:233], v[80:83]
	v_mfma_f32_16x16x32_bf16 v[68:71], v[158:161], v[238:241], v[68:71]
	v_mfma_f32_16x16x32_bf16 v[64:67], v[166:169], v[238:241], v[64:67]
	v_mfma_f32_16x16x32_bf16 v[116:119], v[162:165], v[178:181], v[116:119]
	v_mfma_f32_16x16x32_bf16 v[112:115], v[170:173], v[178:181], v[112:115]
	v_mfma_f32_16x16x32_bf16 v[100:103], v[162:165], v[192:195], v[100:103]
	v_mfma_f32_16x16x32_bf16 v[96:99], v[170:173], v[192:195], v[96:99]
	v_mfma_f32_16x16x32_bf16 v[84:87], v[162:165], v[234:237], v[84:87]
	v_mfma_f32_16x16x32_bf16 v[80:83], v[170:173], v[234:237], v[80:83]
	v_mfma_f32_16x16x32_bf16 v[68:71], v[162:165], v[242:245], v[68:71]
	v_mfma_f32_16x16x32_bf16 v[64:67], v[170:173], v[242:245], v[64:67]
	s_setprio 0
	s_barrier
; #define PG8_STAGE(bufoff, gbase, voff) do { _Pragma("unroll") for (int _i = 0; _i < 2; ++_i) \
;         __builtin_amdgcn_global_load_lds((const unsigned*)((const char*)(gbase) + (voff)[_i]), (PG8_LAS unsigned*)(lds + (bufoff) + ldsw + _i * 8192), 16, 0, 0); } while (0)
; #define PG8_LDA(dst, b, h) do { _Pragma("unroll") for (int m = 0; m < 4; ++m) _Pragma("unroll") for (int k = 0; k < 2; ++k) dst[m][k] = *(const PG8_LAS bf16x8*)(lds + PG8_SA(b, h) + aoff + m * 2048 + k * 1024); } while (0)
; #define PG8_MMA(ai, bj, At, Bt) do { __builtin_amdgcn_s_setprio(1); _Pragma("unroll") for (int m = 0; m < 4; ++m) _Pragma("unroll") for (int n = 0; n < 2; ++n) _Pragma("unroll") for (int k = 0; k < 2; ++k) \
;         acc[ai][bj][m][n] = __builtin_amdgcn_mfma_f32_16x16x32_bf16(Bt[n][k], At[m][k], acc[ai][bj][m][n], 0, 0, 0); __builtin_amdgcn_s_setprio(0); } while (0)
; #define PG8_WAIT_V(n) asm volatile("s_waitcnt vmcnt(" #n ")" ::: "memory")
; #define PG8_WAIT_L(n) asm volatile("s_waitcnt lgkmcnt(" #n ")" ::: "memory")
; #define PG8_BAR __builtin_amdgcn_s_barrier()
; #define PG8_SCHED __builtin_amdgcn_sched_barrier(0)
; template <class Epi, class Sched, bool ALIGN_EPI = false, bool SP2 = false>
; __device__ __forceinline__ void gemm_phase(PG8_LAS unsigned char* lds, const Gemm g, const Sched& S, const Epi& E) {
;     ...
;         for (int t = 0; t < nt; t += 2) {
;     ...
;             PG8_LDA(At, 1, 1); PG8_STAGE(PG8_SB(1, 0), b3, voffB); PG8_STAGE(PG8_SB(1, 1), b3 + hstepB, voffB); PG8_STAGE(PG8_SA(1, 0), a3, voffA);
;             PG8_WAIT_V(8); PG8_WAIT_L(0); PG8_BAR; PG8_MMA(1, 0, At, B0); PG8_MMA(1, 1, At, B1); PG8_BAR; PG8_SCHED;
	ds_read_b128 v[174:177], v145 offset:49152
	ds_read_b128 v[178:181], v145 offset:50176
	ds_read_b128 v[182:185], v145 offset:51200
	ds_read_b128 v[192:195], v145 offset:52224
	ds_read_b128 v[230:233], v145 offset:53248
	ds_read_b128 v[234:237], v145 offset:54272
	ds_read_b128 v[238:241], v145 offset:55296
	ds_read_b128 v[242:245], v145 offset:56320
	s_add_i32 s30, s33, s39
	v_lshl_add_u64 v[186:187], v[186:187], 0, s[94:95]
	s_mov_b32 m0, s30
	global_load_lds_dwordx4 v[186:187], off
	s_add_i32 m0, s30, 0x2000
	s_add_u32 s28, s28, 0x40080
	v_lshl_add_u64 v[186:187], v[196:197], 0, s[94:95]
	s_addc_u32 s29, s29, 0
	s_add_i32 s30, s51, s39
	global_load_lds_dwordx4 v[186:187], off
	s_mov_b32 m0, s30
	v_lshl_add_u64 v[186:187], s[28:29], 0, v[188:189]
	global_load_lds_dwordx4 v[186:187], off
	s_add_i32 m0, s30, 0x2000
	v_lshl_add_u64 v[186:187], s[28:29], 0, v[132:133]
	global_load_lds_dwordx4 v[186:187], off
	s_mov_b32 m0, s47
	v_lshl_add_u64 v[186:187], v[246:247], 0, s[94:95]
	global_load_lds_dwordx4 v[186:187], off
	s_mov_b32 m0, s48
	v_lshl_add_u64 v[186:187], v[248:249], 0, s[94:95]
	global_load_lds_dwordx4 v[186:187], off
	s_waitcnt vmcnt(8)
	s_waitcnt lgkmcnt(0)
	s_barrier
	s_setprio 1
	s_waitcnt lgkmcnt(0)
	v_mfma_f32_16x16x32_bf16 v[60:63], v[138:141], v[174:177], v[60:63]
	v_mfma_f32_16x16x32_bf16 v[56:59], v[150:153], v[174:177], v[56:59]
	v_mfma_f32_16x16x32_bf16 v[44:47], v[138:141], v[182:185], v[44:47]
	v_mfma_f32_16x16x32_bf16 v[40:43], v[150:153], v[182:185], v[40:43]
	v_mfma_f32_16x16x32_bf16 v[28:31], v[138:141], v[230:233], v[28:31]
	v_mfma_f32_16x16x32_bf16 v[24:27], v[150:153], v[230:233], v[24:27]
	v_mfma_f32_16x16x32_bf16 v[12:15], v[138:141], v[238:241], v[12:15]
	v_mfma_f32_16x16x32_bf16 v[8:11], v[150:153], v[238:241], v[8:11]
	v_mfma_f32_16x16x32_bf16 v[60:63], v[146:149], v[178:181], v[60:63]
	v_mfma_f32_16x16x32_bf16 v[56:59], v[154:157], v[178:181], v[56:59]
	v_mfma_f32_16x16x32_bf16 v[44:47], v[146:149], v[192:195], v[44:47]
	v_mfma_f32_16x16x32_bf16 v[40:43], v[154:157], v[192:195], v[40:43]
	v_mfma_f32_16x16x32_bf16 v[28:31], v[146:149], v[234:237], v[28:31]
	v_mfma_f32_16x16x32_bf16 v[24:27], v[154:157], v[234:237], v[24:27]
	v_mfma_f32_16x16x32_bf16 v[12:15], v[146:149], v[242:245], v[12:15]
	v_mfma_f32_16x16x32_bf16 v[8:11], v[154:157], v[242:245], v[8:11]
	s_setprio 0
	s_setprio 1
	v_mfma_f32_16x16x32_bf16 v[52:55], v[158:161], v[174:177], v[52:55]
	v_mfma_f32_16x16x32_bf16 v[48:51], v[166:169], v[174:177], v[48:51]
	v_mfma_f32_16x16x32_bf16 v[36:39], v[158:161], v[182:185], v[36:39]
	v_mfma_f32_16x16x32_bf16 v[32:35], v[166:169], v[182:185], v[32:35]
	v_mfma_f32_16x16x32_bf16 v[20:23], v[158:161], v[230:233], v[20:23]
	v_mfma_f32_16x16x32_bf16 v[16:19], v[166:169], v[230:233], v[16:19]
	v_mfma_f32_16x16x32_bf16 v[4:7], v[158:161], v[238:241], v[4:7]
	v_mfma_f32_16x16x32_bf16 v[0:3], v[166:169], v[238:241], v[0:3]
	v_mfma_f32_16x16x32_bf16 v[52:55], v[162:165], v[178:181], v[52:55]
	v_mfma_f32_16x16x32_bf16 v[48:51], v[170:173], v[178:181], v[48:51]
	v_mfma_f32_16x16x32_bf16 v[36:39], v[162:165], v[192:195], v[36:39]
	v_mfma_f32_16x16x32_bf16 v[32:35], v[170:173], v[192:195], v[32:35]
	v_mfma_f32_16x16x32_bf16 v[20:23], v[162:165], v[234:237], v[20:23]
	v_mfma_f32_16x16x32_bf16 v[16:19], v[170:173], v[234:237], v[16:19]
	v_mfma_f32_16x16x32_bf16 v[4:7], v[162:165], v[242:245], v[4:7]
	v_mfma_f32_16x16x32_bf16 v[0:3], v[170:173], v[242:245], v[0:3]
	s_setprio 0
	s_barrier
	s_add_i32 s19, s19, 2
	s_add_u32 s26, s26, 0x100
	s_addc_u32 s27, s27, 0
	s_add_u32 s9, s9, 0x100
	s_addc_u32 s17, s17, 0
	s_cmp_gt_u32 s19, 13
	s_cbranch_scc0 .LBB0_712
	s_and_b64 vcc, exec, s[14:15]
	s_cbranch_vccz .LBB0_715
	s_barrier

; #define PG8_STAGE(bufoff, gbase, voff) do { _Pragma("unroll") for (int _i = 0; _i < 2; ++_i) \
;         __builtin_amdgcn_global_load_lds((const unsigned*)((const char*)(gbase) + (voff)[_i]), (PG8_LAS unsigned*)(lds + (bufoff) + ldsw + _i * 8192), 16, 0, 0); } while (0)
; #define PG8_LDA(dst, b, h) do { _Pragma("unroll") for (int m = 0; m < 4; ++m) _Pragma("unroll") for (int k = 0; k < 2; ++k) dst[m][k] = *(const PG8_LAS bf16x8*)(lds + PG8_SA(b, h) + aoff + m * 2048 + k * 1024); } while (0)
; #define PG8_LDB(dst, b, h) do { _Pragma("unroll") for (int n = 0; n < 2; ++n) _Pragma("unroll") for (int k = 0; k < 2; ++k) dst[n][k] = *(const PG8_LAS bf16x8*)(lds + PG8_SB(b, h) + boff + n * 2048 + k * 1024); } while (0)
; #define PG8_MMA(ai, bj, At, Bt) do { __builtin_amdgcn_s_setprio(1); _Pragma("unroll") for (int m = 0; m < 4; ++m) _Pragma("unroll") for (int n = 0; n < 2; ++n) _Pragma("unroll") for (int k = 0; k < 2; ++k) \
;         acc[ai][bj][m][n] = __builtin_amdgcn_mfma_f32_16x16x32_bf16(Bt[n][k], At[m][k], acc[ai][bj][m][n], 0, 0, 0); __builtin_amdgcn_s_setprio(0); } while (0)
; #define PG8_WAIT_V(n) asm volatile("s_waitcnt vmcnt(" #n ")" ::: "memory")
; #define PG8_WAIT_L(n) asm volatile("s_waitcnt lgkmcnt(" #n ")" ::: "memory")
; #define PG8_BAR __builtin_amdgcn_s_barrier()
; #define PG8_SCHED __builtin_amdgcn_sched_barrier(0)
; template <class Epi, class Sched, bool ALIGN_EPI = false, bool SP2 = false>
; __device__ __forceinline__ void gemm_phase(PG8_LAS unsigned char* lds, const Gemm g, const Sched& S, const Epi& E) {
;     ...
;             const bool last = (t == nt - 2);
;             const char* a1 = cA + (size_t)(t + 1) * kstep;
;             const char* a2 = last ? nA : cA + (size_t)(t + 2) * kstep; const char* b2 = last ? nB : cB + (size_t)(t + 2) * kstep;
;             const char* a3 = a2 + kstep; const char* b3 = b2 + kstep;
;             if (last && has_next) S.a_ready(nxt);
;             if constexpr (SP2) {
;             PG8_LDB(B0, 0, 0); PG8_LDB(B1, 0, 1); PG8_SCHED; PG8_LDA(At, 0, 0); PG8_STAGE(PG8_SA(1, 1), a1 + hstepA, voffA);
;             PG8_WAIT_V(8); PG8_WAIT_L(0); PG8_BAR; PG8_MMA(0, 0, At, B0); PG8_MMA(0, 1, At, B1); PG8_BAR; PG8_SCHED;
;             PG8_LDA(At, 0, 1); PG8_STAGE(PG8_SB(0, 0), b2, voffB); PG8_STAGE(PG8_SB(0, 1), b2 + hstepB, voffB); PG8_STAGE(PG8_SA(0, 0), a2, voffA);
.LBB0_901:
	v_add_u32_e32 v150, 0x10000, v136
	v_add_u32_e32 v166, 0x14000, v136
	ds_read_b128 v[138:141], v150
	ds_read_b128 v[142:145], v150 offset:1024
	ds_read_b128 v[146:149], v150 offset:2048
	ds_read_b128 v[150:153], v150 offset:3072
	ds_read_b128 v[154:157], v166
	ds_read_b128 v[158:161], v166 offset:1024
	ds_read_b128 v[162:165], v166 offset:2048
	ds_read_b128 v[166:169], v166 offset:3072
	ds_read_b128 v[170:173], v137
	ds_read_b128 v[174:177], v137 offset:1024
	ds_read_b128 v[178:181], v137 offset:2048
	ds_read_b128 v[182:185], v137 offset:3072
	ds_read_b128 v[192:195], v137 offset:4096
	ds_read_b128 v[230:233], v137 offset:5120
	ds_read_b128 v[234:237], v137 offset:6144
	ds_read_b128 v[238:241], v137 offset:7168
	s_add_u32 s44, s34, s38
	s_addc_u32 s45, s35, s39
	s_add_u32 s42, s44, 0x100
	s_addc_u32 s43, s45, 0
	s_and_b64 s[40:41], s[36:37], exec
	s_cselect_b32 s41, s27, s43
	s_cselect_b32 s40, s26, s42
	s_add_u32 s38, s30, s38
	s_addc_u32 s39, s31, s39
	s_add_u32 s38, s38, 0x100
	s_addc_u32 s39, s39, 0
	s_add_i32 s72, 0, 0x10000
	s_and_b64 s[36:37], s[36:37], exec
	s_cselect_b32 s43, s25, s39
	s_cselect_b32 s42, s63, s38
	s_add_i32 s37, 0, 0x14000
	s_add_u32 s46, s44, 0x50080
	s_addc_u32 s47, s45, 0
	s_add_i32 s71, s72, s49
	s_add_i32 m0, s51, 0xc000
	s_add_i32 s74, s51, 0xe000
	s_add_i32 s68, s71, 0x2000
	s_add_u32 s44, s42, 0x10000
	s_addc_u32 s45, s43, 0
	s_add_i32 s70, s37, s49
	s_add_i32 s69, s70, 0x2000
	s_add_i32 s67, 0, 0x18000
	s_add_i32 s66, 0, 0x1c000
	s_add_u32 s38, s40, 0x50000
	s_addc_u32 s39, s41, 0
	s_add_i32 s65, s67, s49
	s_add_i32 s64, s65, 0x2000
	s_add_u32 s36, s42, 0x10080
	s_addc_u32 s37, s43, 0
	s_add_i32 s73, s66, s49
	s_add_i32 s72, s73, 0x2000
	v_lshl_add_u64 v[186:187], s[46:47], 0, v[132:133]
	global_load_lds_dwordx4 v[186:187], off
	s_mov_b32 m0, s74
	v_lshl_add_u64 v[186:187], s[46:47], 0, v[130:131]
	global_load_lds_dwordx4 v[186:187], off
	s_waitcnt vmcnt(8)
	s_waitcnt lgkmcnt(0)
	s_barrier
	s_setprio 1
	s_waitcnt lgkmcnt(0)
	v_mfma_f32_16x16x32_bf16 v[124:127], v[138:141], v[170:173], v[124:127]
	v_mfma_f32_16x16x32_bf16 v[120:123], v[146:149], v[170:173], v[120:123]
	v_mfma_f32_16x16x32_bf16 v[116:119], v[138:141], v[178:181], v[116:119]
	v_mfma_f32_16x16x32_bf16 v[112:115], v[146:149], v[178:181], v[112:115]
	v_mfma_f32_16x16x32_bf16 v[100:103], v[138:141], v[192:195], v[100:103]
	v_mfma_f32_16x16x32_bf16 v[96:99], v[146:149], v[192:195], v[96:99]
	v_mfma_f32_16x16x32_bf16 v[84:87], v[138:141], v[234:237], v[84:87]
	v_mfma_f32_16x16x32_bf16 v[80:83], v[146:149], v[234:237], v[80:83]
	v_mfma_f32_16x16x32_bf16 v[124:127], v[142:145], v[174:177], v[124:127]
	v_mfma_f32_16x16x32_bf16 v[120:123], v[150:153], v[174:177], v[120:123]
	v_mfma_f32_16x16x32_bf16 v[116:119], v[142:145], v[182:185], v[116:119]
	v_mfma_f32_16x16x32_bf16 v[112:115], v[150:153], v[182:185], v[112:115]
	v_mfma_f32_16x16x32_bf16 v[100:103], v[142:145], v[230:233], v[100:103]
	v_mfma_f32_16x16x32_bf16 v[96:99], v[150:153], v[230:233], v[96:99]
	v_mfma_f32_16x16x32_bf16 v[84:87], v[142:145], v[238:241], v[84:87]
	v_mfma_f32_16x16x32_bf16 v[80:83], v[150:153], v[238:241], v[80:83]
	s_setprio 0
	s_setprio 1
	v_mfma_f32_16x16x32_bf16 v[108:111], v[154:157], v[170:173], v[108:111]
	v_mfma_f32_16x16x32_bf16 v[104:107], v[162:165], v[170:173], v[104:107]
	v_mfma_f32_16x16x32_bf16 v[92:95], v[154:157], v[178:181], v[92:95]
	v_mfma_f32_16x16x32_bf16 v[88:91], v[162:165], v[178:181], v[88:91]
	v_mfma_f32_16x16x32_bf16 v[76:79], v[154:157], v[192:195], v[76:79]
	v_mfma_f32_16x16x32_bf16 v[72:75], v[162:165], v[192:195], v[72:75]
	v_mfma_f32_16x16x32_bf16 v[68:71], v[154:157], v[234:237], v[68:71]
	v_mfma_f32_16x16x32_bf16 v[64:67], v[162:165], v[234:237], v[64:67]
	v_mfma_f32_16x16x32_bf16 v[108:111], v[158:161], v[174:177], v[108:111]
	v_mfma_f32_16x16x32_bf16 v[104:107], v[166:169], v[174:177], v[104:107]
	v_mfma_f32_16x16x32_bf16 v[92:95], v[158:161], v[182:185], v[92:95]
	v_mfma_f32_16x16x32_bf16 v[88:91], v[166:169], v[182:185], v[88:91]
	v_mfma_f32_16x16x32_bf16 v[76:79], v[158:161], v[230:233], v[76:79]
	v_mfma_f32_16x16x32_bf16 v[72:75], v[166:169], v[230:233], v[72:75]
	v_mfma_f32_16x16x32_bf16 v[68:71], v[158:161], v[238:241], v[68:71]
	v_mfma_f32_16x16x32_bf16 v[64:67], v[166:169], v[238:241], v[64:67]
	s_setprio 0
	s_barrier
	ds_read_b128 v[170:173], v137 offset:16384
	ds_read_b128 v[174:177], v137 offset:17408
	ds_read_b128 v[178:181], v137 offset:18432
	ds_read_b128 v[182:185], v137 offset:19456
	ds_read_b128 v[192:195], v137 offset:20480
	ds_read_b128 v[230:233], v137 offset:21504
	ds_read_b128 v[234:237], v137 offset:22528
	ds_read_b128 v[238:241], v137 offset:23552
	s_mov_b32 m0, s71
	v_lshl_add_u64 v[186:187], s[42:43], 0, v[188:189]
	global_load_lds_dwordx4 v[186:187], off
	v_lshl_add_u64 v[196:197], s[42:43], 0, v[128:129]
	s_mov_b32 m0, s68
	v_lshl_add_u64 v[242:243], s[44:45], 0, v[188:189]
	global_load_lds_dwordx4 v[196:197], off
	s_mov_b32 m0, s70
	v_lshl_add_u64 v[244:245], s[40:41], 0, v[130:131]
	global_load_lds_dwordx4 v[242:243], off
	s_mov_b32 m0, s69
	v_lshl_add_u64 v[242:243], s[44:45], 0, v[128:129]
	global_load_lds_dwordx4 v[242:243], off
	s_mov_b32 m0, s51
	v_lshl_add_u64 v[242:243], s[40:41], 0, v[132:133]
	global_load_lds_dwordx4 v[242:243], off
	s_mov_b32 m0, s52
	s_nop 0
	global_load_lds_dwordx4 v[244:245], off
	s_waitcnt vmcnt(8)
	s_waitcnt lgkmcnt(0)
	s_barrier
; #define PG8_STAGE(bufoff, gbase, voff) do { _Pragma("unroll") for (int _i = 0; _i < 2; ++_i) \
;         __builtin_amdgcn_global_load_lds((const unsigned*)((const char*)(gbase) + (voff)[_i]), (PG8_LAS unsigned*)(lds + (bufoff) + ldsw + _i * 8192), 16, 0, 0); } while (0)
; #define PG8_LDA(dst, b, h) do { _Pragma("unroll") for (int m = 0; m < 4; ++m) _Pragma("unroll") for (int k = 0; k < 2; ++k) dst[m][k] = *(const PG8_LAS bf16x8*)(lds + PG8_SA(b, h) + aoff + m * 2048 + k * 1024); } while (0)
; #define PG8_LDB(dst, b, h) do { _Pragma("unroll") for (int n = 0; n < 2; ++n) _Pragma("unroll") for (int k = 0; k < 2; ++k) dst[n][k] = *(const PG8_LAS bf16x8*)(lds + PG8_SB(b, h) + boff + n * 2048 + k * 1024); } while (0)
; #define PG8_MMA(ai, bj, At, Bt) do { __builtin_amdgcn_s_setprio(1); _Pragma("unroll") for (int m = 0; m < 4; ++m) _Pragma("unroll") for (int n = 0; n < 2; ++n) _Pragma("unroll") for (int k = 0; k < 2; ++k) \
;         acc[ai][bj][m][n] = __builtin_amdgcn_mfma_f32_16x16x32_bf16(Bt[n][k], At[m][k], acc[ai][bj][m][n], 0, 0, 0); __builtin_amdgcn_s_setprio(0); } while (0)
; #define PG8_WAIT_V(n) asm volatile("s_waitcnt vmcnt(" #n ")" ::: "memory")
; #define PG8_WAIT_L(n) asm volatile("s_waitcnt lgkmcnt(" #n ")" ::: "memory")
; #define PG8_BAR __builtin_amdgcn_s_barrier()
; #define PG8_SCHED __builtin_amdgcn_sched_barrier(0)
; template <class Epi, class Sched, bool ALIGN_EPI = false, bool SP2 = false>
; __device__ __forceinline__ void gemm_phase(PG8_LAS unsigned char* lds, const Gemm g, const Sched& S, const Epi& E) {
;     ...
;             PG8_WAIT_V(8); PG8_WAIT_L(0); PG8_BAR; PG8_MMA(1, 0, At, B0); PG8_MMA(1, 1, At, B1); PG8_BAR; PG8_SCHED;
;             PG8_LDB(B0, 1, 0); PG8_LDB(B1, 1, 1); PG8_SCHED; PG8_LDA(At, 1, 0); PG8_STAGE(PG8_SA(0, 1), a2 + hstepA, voffA);
;             PG8_WAIT_V(8); PG8_WAIT_L(0); PG8_BAR; PG8_MMA(0, 0, At, B0); PG8_MMA(0, 1, At, B1); PG8_BAR; PG8_SCHED;
	s_setprio 1
	s_waitcnt lgkmcnt(0)
	v_mfma_f32_16x16x32_bf16 v[60:63], v[138:141], v[170:173], v[60:63]
	v_mfma_f32_16x16x32_bf16 v[56:59], v[146:149], v[170:173], v[56:59]
	v_mfma_f32_16x16x32_bf16 v[52:55], v[138:141], v[178:181], v[52:55]
	v_mfma_f32_16x16x32_bf16 v[48:51], v[146:149], v[178:181], v[48:51]
	v_mfma_f32_16x16x32_bf16 v[36:39], v[138:141], v[192:195], v[36:39]
	v_mfma_f32_16x16x32_bf16 v[32:35], v[146:149], v[192:195], v[32:35]
	v_mfma_f32_16x16x32_bf16 v[20:23], v[138:141], v[234:237], v[20:23]
	v_mfma_f32_16x16x32_bf16 v[16:19], v[146:149], v[234:237], v[16:19]
	v_mfma_f32_16x16x32_bf16 v[60:63], v[142:145], v[174:177], v[60:63]
	v_mfma_f32_16x16x32_bf16 v[56:59], v[150:153], v[174:177], v[56:59]
	v_mfma_f32_16x16x32_bf16 v[52:55], v[142:145], v[182:185], v[52:55]
	v_mfma_f32_16x16x32_bf16 v[48:51], v[150:153], v[182:185], v[48:51]
	v_mfma_f32_16x16x32_bf16 v[36:39], v[142:145], v[230:233], v[36:39]
	v_mfma_f32_16x16x32_bf16 v[32:35], v[150:153], v[230:233], v[32:35]
	v_mfma_f32_16x16x32_bf16 v[20:23], v[142:145], v[238:241], v[20:23]
	v_mfma_f32_16x16x32_bf16 v[16:19], v[150:153], v[238:241], v[16:19]
	s_setprio 0
	s_setprio 1
	v_mfma_f32_16x16x32_bf16 v[44:47], v[154:157], v[170:173], v[44:47]
	v_mfma_f32_16x16x32_bf16 v[40:43], v[162:165], v[170:173], v[40:43]
	v_mfma_f32_16x16x32_bf16 v[28:31], v[154:157], v[178:181], v[28:31]
	v_mfma_f32_16x16x32_bf16 v[24:27], v[162:165], v[178:181], v[24:27]
	v_mfma_f32_16x16x32_bf16 v[12:15], v[154:157], v[192:195], v[12:15]
	v_mfma_f32_16x16x32_bf16 v[8:11], v[162:165], v[192:195], v[8:11]
	v_mfma_f32_16x16x32_bf16 v[4:7], v[154:157], v[234:237], v[4:7]
	v_mfma_f32_16x16x32_bf16 v[0:3], v[162:165], v[234:237], v[0:3]
	v_mfma_f32_16x16x32_bf16 v[44:47], v[158:161], v[174:177], v[44:47]
	v_mfma_f32_16x16x32_bf16 v[40:43], v[166:169], v[174:177], v[40:43]
	v_mfma_f32_16x16x32_bf16 v[28:31], v[158:161], v[182:185], v[28:31]
	v_mfma_f32_16x16x32_bf16 v[24:27], v[166:169], v[182:185], v[24:27]
	v_mfma_f32_16x16x32_bf16 v[12:15], v[158:161], v[230:233], v[12:15]
	v_mfma_f32_16x16x32_bf16 v[8:11], v[166:169], v[230:233], v[8:11]
	v_mfma_f32_16x16x32_bf16 v[4:7], v[158:161], v[238:241], v[4:7]
	v_mfma_f32_16x16x32_bf16 v[0:3], v[166:169], v[238:241], v[0:3]
	s_setprio 0
	s_barrier
	v_add_u32_e32 v150, 0x18000, v136
	v_add_u32_e32 v166, 0x1c000, v136
	ds_read_b128 v[138:141], v150
	ds_read_b128 v[142:145], v150 offset:1024
	ds_read_b128 v[146:149], v150 offset:2048
	ds_read_b128 v[150:153], v150 offset:3072
	ds_read_b128 v[154:157], v166
	ds_read_b128 v[158:161], v166 offset:1024
	ds_read_b128 v[162:165], v166 offset:2048
	ds_read_b128 v[166:169], v166 offset:3072
	ds_read_b128 v[170:173], v137 offset:32768
	ds_read_b128 v[174:177], v137 offset:33792
	ds_read_b128 v[178:181], v137 offset:34816
	ds_read_b128 v[182:185], v137 offset:35840
	ds_read_b128 v[192:195], v137 offset:36864
	ds_read_b128 v[230:233], v137 offset:37888
	ds_read_b128 v[234:237], v137 offset:38912
	ds_read_b128 v[238:241], v137 offset:39936
	s_mov_b32 m0, s53
	v_lshl_add_u64 v[246:247], s[38:39], 0, v[132:133]
	global_load_lds_dwordx4 v[246:247], off
	s_mov_b32 m0, s54
	v_lshl_add_u64 v[246:247], s[38:39], 0, v[130:131]
	global_load_lds_dwordx4 v[246:247], off
	s_waitcnt vmcnt(8)
	s_waitcnt lgkmcnt(0)
	s_barrier
	s_setprio 1
	s_waitcnt lgkmcnt(0)
	v_mfma_f32_16x16x32_bf16 v[124:127], v[138:141], v[170:173], v[124:127]
	v_mfma_f32_16x16x32_bf16 v[120:123], v[146:149], v[170:173], v[120:123]
	v_mfma_f32_16x16x32_bf16 v[116:119], v[138:141], v[178:181], v[116:119]
	v_mfma_f32_16x16x32_bf16 v[112:115], v[146:149], v[178:181], v[112:115]
	v_mfma_f32_16x16x32_bf16 v[100:103], v[138:141], v[192:195], v[100:103]
	v_mfma_f32_16x16x32_bf16 v[96:99], v[146:149], v[192:195], v[96:99]
	v_mfma_f32_16x16x32_bf16 v[84:87], v[138:141], v[234:237], v[84:87]
	v_mfma_f32_16x16x32_bf16 v[80:83], v[146:149], v[234:237], v[80:83]
	v_mfma_f32_16x16x32_bf16 v[124:127], v[142:145], v[174:177], v[124:127]
	v_mfma_f32_16x16x32_bf16 v[120:123], v[150:153], v[174:177], v[120:123]
	v_mfma_f32_16x16x32_bf16 v[116:119], v[142:145], v[182:185], v[116:119]
	v_mfma_f32_16x16x32_bf16 v[112:115], v[150:153], v[182:185], v[112:115]
	v_mfma_f32_16x16x32_bf16 v[100:103], v[142:145], v[230:233], v[100:103]
	v_mfma_f32_16x16x32_bf16 v[96:99], v[150:153], v[230:233], v[96:99]
	v_mfma_f32_16x16x32_bf16 v[84:87], v[142:145], v[238:241], v[84:87]
	v_mfma_f32_16x16x32_bf16 v[80:83], v[150:153], v[238:241], v[80:83]
	s_setprio 0
	s_setprio 1
	v_mfma_f32_16x16x32_bf16 v[108:111], v[154:157], v[170:173], v[108:111]
	v_mfma_f32_16x16x32_bf16 v[104:107], v[162:165], v[170:173], v[104:107]
	v_mfma_f32_16x16x32_bf16 v[92:95], v[154:157], v[178:181], v[92:95]
	v_mfma_f32_16x16x32_bf16 v[88:91], v[162:165], v[178:181], v[88:91]
	v_mfma_f32_16x16x32_bf16 v[76:79], v[154:157], v[192:195], v[76:79]
	v_mfma_f32_16x16x32_bf16 v[72:75], v[162:165], v[192:195], v[72:75]
	v_mfma_f32_16x16x32_bf16 v[68:71], v[154:157], v[234:237], v[68:71]
	v_mfma_f32_16x16x32_bf16 v[64:67], v[162:165], v[234:237], v[64:67]
	v_mfma_f32_16x16x32_bf16 v[108:111], v[158:161], v[174:177], v[108:111]
	v_mfma_f32_16x16x32_bf16 v[104:107], v[166:169], v[174:177], v[104:107]
	v_mfma_f32_16x16x32_bf16 v[92:95], v[158:161], v[182:185], v[92:95]
	v_mfma_f32_16x16x32_bf16 v[88:91], v[166:169], v[182:185], v[88:91]
	v_mfma_f32_16x16x32_bf16 v[76:79], v[158:161], v[230:233], v[76:79]
	v_mfma_f32_16x16x32_bf16 v[72:75], v[166:169], v[230:233], v[72:75]
	v_mfma_f32_16x16x32_bf16 v[68:71], v[158:161], v[238:241], v[68:71]
	v_mfma_f32_16x16x32_bf16 v[64:67], v[166:169], v[238:241], v[64:67]
	s_setprio 0
	s_barrier
; #define PG8_STAGE(bufoff, gbase, voff) do { _Pragma("unroll") for (int _i = 0; _i < 2; ++_i) \
;         __builtin_amdgcn_global_load_lds((const unsigned*)((const char*)(gbase) + (voff)[_i]), (PG8_LAS unsigned*)(lds + (bufoff) + ldsw + _i * 8192), 16, 0, 0); } while (0)
; #define PG8_LDA(dst, b, h) do { _Pragma("unroll") for (int m = 0; m < 4; ++m) _Pragma("unroll") for (int k = 0; k < 2; ++k) dst[m][k] = *(const PG8_LAS bf16x8*)(lds + PG8_SA(b, h) + aoff + m * 2048 + k * 1024); } while (0)
; #define PG8_MMA(ai, bj, At, Bt) do { __builtin_amdgcn_s_setprio(1); _Pragma("unroll") for (int m = 0; m < 4; ++m) _Pragma("unroll") for (int n = 0; n < 2; ++n) _Pragma("unroll") for (int k = 0; k < 2; ++k) \
;         acc[ai][bj][m][n] = __builtin_amdgcn_mfma_f32_16x16x32_bf16(Bt[n][k], At[m][k], acc[ai][bj][m][n], 0, 0, 0); __builtin_amdgcn_s_setprio(0); } while (0)
; #define PG8_WAIT_V(n) asm volatile("s_waitcnt vmcnt(" #n ")" ::: "memory")
; #define PG8_WAIT_L(n) asm volatile("s_waitcnt lgkmcnt(" #n ")" ::: "memory")
; #define PG8_BAR __builtin_amdgcn_s_barrier()
; #define PG8_SCHED __builtin_amdgcn_sched_barrier(0)
; template <class Epi, class Sched, bool ALIGN_EPI = false, bool SP2 = false>
; __device__ __forceinline__ void gemm_phase(PG8_LAS unsigned char* lds, const Gemm g, const Sched& S, const Epi& E) {
;     ...
;         for (int t = 0; t < nt; t += 2) {
;     ...
;             PG8_LDA(At, 1, 1); PG8_STAGE(PG8_SB(1, 0), b3, voffB); PG8_STAGE(PG8_SB(1, 1), b3 + hstepB, voffB); PG8_STAGE(PG8_SA(1, 0), a3, voffA);
;             PG8_WAIT_V(8); PG8_WAIT_L(0); PG8_BAR; PG8_MMA(1, 0, At, B0); PG8_MMA(1, 1, At, B1); PG8_BAR; PG8_SCHED;
	ds_read_b128 v[170:173], v137 offset:49152
	ds_read_b128 v[174:177], v137 offset:50176
	ds_read_b128 v[178:181], v137 offset:51200
	ds_read_b128 v[182:185], v137 offset:52224
	ds_read_b128 v[192:195], v137 offset:53248
	ds_read_b128 v[230:233], v137 offset:54272
	ds_read_b128 v[234:237], v137 offset:55296
	ds_read_b128 v[238:241], v137 offset:56320
	s_mov_b32 m0, s65
	v_lshl_add_u64 v[186:187], v[186:187], 0, s[94:95]
	global_load_lds_dwordx4 v[186:187], off
	s_mov_b32 m0, s64
	v_lshl_add_u64 v[186:187], v[196:197], 0, s[94:95]
	global_load_lds_dwordx4 v[186:187], off
	s_mov_b32 m0, s73
	v_lshl_add_u64 v[186:187], s[36:37], 0, v[188:189]
	global_load_lds_dwordx4 v[186:187], off
	s_mov_b32 m0, s72
	v_lshl_add_u64 v[186:187], s[36:37], 0, v[128:129]
	global_load_lds_dwordx4 v[186:187], off
	s_mov_b32 m0, s56
	v_lshl_add_u64 v[186:187], v[242:243], 0, s[94:95]
	global_load_lds_dwordx4 v[186:187], off
	s_mov_b32 m0, s57
	v_lshl_add_u64 v[186:187], v[244:245], 0, s[94:95]
	global_load_lds_dwordx4 v[186:187], off
	s_waitcnt vmcnt(8)
	s_waitcnt lgkmcnt(0)
	s_barrier
	s_setprio 1
	s_waitcnt lgkmcnt(0)
	v_mfma_f32_16x16x32_bf16 v[60:63], v[138:141], v[170:173], v[60:63]
	v_mfma_f32_16x16x32_bf16 v[56:59], v[146:149], v[170:173], v[56:59]
	v_mfma_f32_16x16x32_bf16 v[52:55], v[138:141], v[178:181], v[52:55]
	v_mfma_f32_16x16x32_bf16 v[48:51], v[146:149], v[178:181], v[48:51]
	v_mfma_f32_16x16x32_bf16 v[36:39], v[138:141], v[192:195], v[36:39]
	v_mfma_f32_16x16x32_bf16 v[32:35], v[146:149], v[192:195], v[32:35]
	v_mfma_f32_16x16x32_bf16 v[20:23], v[138:141], v[234:237], v[20:23]
	v_mfma_f32_16x16x32_bf16 v[16:19], v[146:149], v[234:237], v[16:19]
	v_mfma_f32_16x16x32_bf16 v[60:63], v[142:145], v[174:177], v[60:63]
	v_mfma_f32_16x16x32_bf16 v[56:59], v[150:153], v[174:177], v[56:59]
	v_mfma_f32_16x16x32_bf16 v[52:55], v[142:145], v[182:185], v[52:55]
	v_mfma_f32_16x16x32_bf16 v[48:51], v[150:153], v[182:185], v[48:51]
	v_mfma_f32_16x16x32_bf16 v[36:39], v[142:145], v[230:233], v[36:39]
	v_mfma_f32_16x16x32_bf16 v[32:35], v[150:153], v[230:233], v[32:35]
	v_mfma_f32_16x16x32_bf16 v[20:23], v[142:145], v[238:241], v[20:23]
	v_mfma_f32_16x16x32_bf16 v[16:19], v[150:153], v[238:241], v[16:19]
	s_setprio 0
	s_setprio 1
	v_mfma_f32_16x16x32_bf16 v[44:47], v[154:157], v[170:173], v[44:47]
	v_mfma_f32_16x16x32_bf16 v[40:43], v[162:165], v[170:173], v[40:43]
	v_mfma_f32_16x16x32_bf16 v[28:31], v[154:157], v[178:181], v[28:31]
	v_mfma_f32_16x16x32_bf16 v[24:27], v[162:165], v[178:181], v[24:27]
	v_mfma_f32_16x16x32_bf16 v[12:15], v[154:157], v[192:195], v[12:15]
	v_mfma_f32_16x16x32_bf16 v[8:11], v[162:165], v[192:195], v[8:11]
	v_mfma_f32_16x16x32_bf16 v[4:7], v[154:157], v[234:237], v[4:7]
	v_mfma_f32_16x16x32_bf16 v[0:3], v[162:165], v[234:237], v[0:3]
	v_mfma_f32_16x16x32_bf16 v[44:47], v[158:161], v[174:177], v[44:47]
	v_mfma_f32_16x16x32_bf16 v[40:43], v[166:169], v[174:177], v[40:43]
	v_mfma_f32_16x16x32_bf16 v[28:31], v[158:161], v[182:185], v[28:31]
	v_mfma_f32_16x16x32_bf16 v[24:27], v[166:169], v[182:185], v[24:27]
	v_mfma_f32_16x16x32_bf16 v[12:15], v[158:161], v[230:233], v[12:15]
	v_mfma_f32_16x16x32_bf16 v[8:11], v[166:169], v[230:233], v[8:11]
	v_mfma_f32_16x16x32_bf16 v[4:7], v[158:161], v[238:241], v[4:7]
	v_mfma_f32_16x16x32_bf16 v[0:3], v[166:169], v[238:241], v[0:3]
	s_setprio 0
	s_barrier
	s_andn2_b64 vcc, exec, s[8:9]
	s_mov_b64 s[36:37], -1
	s_mov_b64 s[8:9], 0
	s_mov_b64 s[38:39], 0x100
	s_cbranch_vccz .LBB0_901
	s_and_b64 vcc, exec, s[20:21]
	s_cbranch_vccz .LBB0_904
	s_barrier

; #define PG8_STAGE(bufoff, gbase, voff) do { _Pragma("unroll") for (int _i = 0; _i < 2; ++_i) \
;         __builtin_amdgcn_global_load_lds((const unsigned*)((const char*)(gbase) + (voff)[_i]), (PG8_LAS unsigned*)(lds + (bufoff) + ldsw + _i * 8192), 16, 0, 0); } while (0)
; #define PG8_LDA(dst, b, h) do { _Pragma("unroll") for (int m = 0; m < 4; ++m) _Pragma("unroll") for (int k = 0; k < 2; ++k) dst[m][k] = *(const PG8_LAS bf16x8*)(lds + PG8_SA(b, h) + aoff + m * 2048 + k * 1024); } while (0)
; #define PG8_LDB(dst, b, h) do { _Pragma("unroll") for (int n = 0; n < 2; ++n) _Pragma("unroll") for (int k = 0; k < 2; ++k) dst[n][k] = *(const PG8_LAS bf16x8*)(lds + PG8_SB(b, h) + boff + n * 2048 + k * 1024); } while (0)
; #define PG8_MMA(ai, bj, At, Bt) do { __builtin_amdgcn_s_setprio(1); _Pragma("unroll") for (int m = 0; m < 4; ++m) _Pragma("unroll") for (int n = 0; n < 2; ++n) _Pragma("unroll") for (int k = 0; k < 2; ++k) \
;         acc[ai][bj][m][n] = __builtin_amdgcn_mfma_f32_16x16x32_bf16(Bt[n][k], At[m][k], acc[ai][bj][m][n], 0, 0, 0); __builtin_amdgcn_s_setprio(0); } while (0)
; #define PG8_WAIT_V(n) asm volatile("s_waitcnt vmcnt(" #n ")" ::: "memory")
; #define PG8_WAIT_L(n) asm volatile("s_waitcnt lgkmcnt(" #n ")" ::: "memory")
; #define PG8_BAR __builtin_amdgcn_s_barrier()
; #define PG8_SCHED __builtin_amdgcn_sched_barrier(0)
; template <class Epi, class Sched, bool ALIGN_EPI = false, bool SP2 = false>
; __device__ __forceinline__ void gemm_phase(PG8_LAS unsigned char* lds, const Gemm g, const Sched& S, const Epi& E) {
;     ...
;             const bool last = (t == nt - 2);
;             const char* a1 = cA + (size_t)(t + 1) * kstep;
;             const char* a2 = last ? nA : cA + (size_t)(t + 2) * kstep; const char* b2 = last ? nB : cB + (size_t)(t + 2) * kstep;
;             const char* a3 = a2 + kstep; const char* b3 = b2 + kstep;
;             if (last && has_next) S.a_ready(nxt);
;             if constexpr (SP2) {
;             PG8_LDB(B0, 0, 0); PG8_LDB(B1, 0, 1); PG8_SCHED; PG8_LDA(At, 0, 0); PG8_STAGE(PG8_SA(1, 1), a1 + hstepA, voffA);
;             PG8_WAIT_V(8); PG8_WAIT_L(0); PG8_BAR; PG8_MMA(0, 0, At, B0); PG8_MMA(0, 1, At, B1); PG8_BAR; PG8_SCHED;
;             PG8_LDA(At, 0, 1); PG8_STAGE(PG8_SB(0, 0), b2, voffB); PG8_STAGE(PG8_SB(0, 1), b2 + hstepB, voffB); PG8_STAGE(PG8_SA(0, 0), a2, voffA);
.LBB0_1642:
	v_add_u32_e32 v150, 0x10000, v148
	v_add_u32_e32 v166, 0x14000, v148
	ds_read_b128 v[128:131], v150
	ds_read_b128 v[138:141], v150 offset:1024
	ds_read_b128 v[142:145], v150 offset:2048
	ds_read_b128 v[150:153], v150 offset:3072
	ds_read_b128 v[154:157], v166
	ds_read_b128 v[158:161], v166 offset:1024
	ds_read_b128 v[162:165], v166 offset:2048
	ds_read_b128 v[166:169], v166 offset:3072
	ds_read_b128 v[170:173], v149
	ds_read_b128 v[174:177], v149 offset:1024
	ds_read_b128 v[178:181], v149 offset:2048
	ds_read_b128 v[182:185], v149 offset:3072
	ds_read_b128 v[192:195], v149 offset:4096
	ds_read_b128 v[230:233], v149 offset:5120
	ds_read_b128 v[234:237], v149 offset:6144
	ds_read_b128 v[238:241], v149 offset:7168
	s_add_i32 s74, s28, 2
	s_add_u32 s75, s26, 0x80
	s_addc_u32 s29, s27, 0
	s_add_i32 s78, 0, 0x10000
	s_cmp_eq_u32 s54, s28
	s_cselect_b32 s29, s9, s29
	s_cselect_b32 s28, s8, s75
	s_cselect_b32 s77, s25, s73
	s_cselect_b32 s76, s24, s72
	s_add_i32 s75, 0, 0x14000
	v_lshl_add_u64 v[186:187], s[26:27], 0, v[134:135]
	s_add_i32 m0, s36, 0xc000
	global_load_lds_dwordx4 v[186:187], off
	s_add_i32 m0, s36, 0xe000
	v_lshl_add_u64 v[186:187], s[26:27], 0, v[136:137]
	global_load_lds_dwordx4 v[186:187], off
	s_waitcnt vmcnt(8)
	s_waitcnt lgkmcnt(0)
	s_barrier
	s_setprio 1
	s_waitcnt lgkmcnt(0)
	v_mfma_f32_16x16x32_bf16 v[124:127], v[128:131], v[170:173], v[124:127]
	v_mfma_f32_16x16x32_bf16 v[96:99], v[142:145], v[170:173], v[96:99]
	v_mfma_f32_16x16x32_bf16 v[120:123], v[128:131], v[178:181], v[120:123]
	v_mfma_f32_16x16x32_bf16 v[92:95], v[142:145], v[178:181], v[92:95]
	v_mfma_f32_16x16x32_bf16 v[116:119], v[128:131], v[192:195], v[116:119]
	v_mfma_f32_16x16x32_bf16 v[88:91], v[142:145], v[192:195], v[88:91]
	v_mfma_f32_16x16x32_bf16 v[112:115], v[128:131], v[234:237], v[112:115]
	v_mfma_f32_16x16x32_bf16 v[80:83], v[142:145], v[234:237], v[80:83]
	v_mfma_f32_16x16x32_bf16 v[124:127], v[138:141], v[174:177], v[124:127]
	v_mfma_f32_16x16x32_bf16 v[96:99], v[150:153], v[174:177], v[96:99]
	v_mfma_f32_16x16x32_bf16 v[120:123], v[138:141], v[182:185], v[120:123]
	v_mfma_f32_16x16x32_bf16 v[92:95], v[150:153], v[182:185], v[92:95]
	v_mfma_f32_16x16x32_bf16 v[116:119], v[138:141], v[230:233], v[116:119]
	v_mfma_f32_16x16x32_bf16 v[88:91], v[150:153], v[230:233], v[88:91]
	v_mfma_f32_16x16x32_bf16 v[112:115], v[138:141], v[238:241], v[112:115]
	v_mfma_f32_16x16x32_bf16 v[80:83], v[150:153], v[238:241], v[80:83]
	s_setprio 0
	s_setprio 1
	v_mfma_f32_16x16x32_bf16 v[72:75], v[154:157], v[170:173], v[72:75]
	v_mfma_f32_16x16x32_bf16 v[44:47], v[162:165], v[170:173], v[44:47]
	v_mfma_f32_16x16x32_bf16 v[64:67], v[154:157], v[178:181], v[64:67]
	v_mfma_f32_16x16x32_bf16 v[36:39], v[162:165], v[178:181], v[36:39]
	v_mfma_f32_16x16x32_bf16 v[56:59], v[154:157], v[192:195], v[56:59]
	v_mfma_f32_16x16x32_bf16 v[28:31], v[162:165], v[192:195], v[28:31]
	v_mfma_f32_16x16x32_bf16 v[48:51], v[154:157], v[234:237], v[48:51]
	v_mfma_f32_16x16x32_bf16 v[20:23], v[162:165], v[234:237], v[20:23]
	v_mfma_f32_16x16x32_bf16 v[72:75], v[158:161], v[174:177], v[72:75]
	v_mfma_f32_16x16x32_bf16 v[44:47], v[166:169], v[174:177], v[44:47]
	v_mfma_f32_16x16x32_bf16 v[64:67], v[158:161], v[182:185], v[64:67]
	v_mfma_f32_16x16x32_bf16 v[36:39], v[166:169], v[182:185], v[36:39]
	v_mfma_f32_16x16x32_bf16 v[56:59], v[158:161], v[230:233], v[56:59]
	v_mfma_f32_16x16x32_bf16 v[28:31], v[166:169], v[230:233], v[28:31]
	v_mfma_f32_16x16x32_bf16 v[48:51], v[158:161], v[238:241], v[48:51]
	v_mfma_f32_16x16x32_bf16 v[20:23], v[166:169], v[238:241], v[20:23]
	s_setprio 0
	s_barrier
	ds_read_b128 v[170:173], v149 offset:16384
	ds_read_b128 v[174:177], v149 offset:17408
	ds_read_b128 v[178:181], v149 offset:18432
	ds_read_b128 v[182:185], v149 offset:19456
	ds_read_b128 v[192:195], v149 offset:20480
	ds_read_b128 v[230:233], v149 offset:21504
	ds_read_b128 v[234:237], v149 offset:22528
	ds_read_b128 v[238:241], v149 offset:23552
	s_add_i32 s78, s78, s30
	v_lshl_add_u64 v[186:187], s[76:77], 0, v[188:189]
	s_mov_b32 m0, s78
	global_load_lds_dwordx4 v[186:187], off
	s_add_i32 m0, s78, 0x2000
	v_lshl_add_u64 v[196:197], s[76:77], 0, v[132:133]
	s_add_u32 s76, s76, s44
	s_addc_u32 s77, s77, 0
	s_add_i32 s75, s75, s30
	global_load_lds_dwordx4 v[196:197], off
	v_lshl_add_u64 v[242:243], s[76:77], 0, v[188:189]
	s_mov_b32 m0, s75
	v_lshl_add_u64 v[244:245], s[76:77], 0, v[132:133]
	global_load_lds_dwordx4 v[242:243], off
	s_add_i32 m0, s75, 0x2000
	v_lshl_add_u64 v[246:247], s[28:29], 0, v[188:189]
	global_load_lds_dwordx4 v[244:245], off
	s_mov_b32 m0, s36
	v_lshl_add_u64 v[248:249], s[28:29], 0, v[132:133]
	global_load_lds_dwordx4 v[246:247], off
	s_mov_b32 m0, s37
	s_nop 0
	global_load_lds_dwordx4 v[248:249], off
	s_waitcnt vmcnt(8)
	s_waitcnt lgkmcnt(0)
	s_barrier
; #define PG8_STAGE(bufoff, gbase, voff) do { _Pragma("unroll") for (int _i = 0; _i < 2; ++_i) \
;         __builtin_amdgcn_global_load_lds((const unsigned*)((const char*)(gbase) + (voff)[_i]), (PG8_LAS unsigned*)(lds + (bufoff) + ldsw + _i * 8192), 16, 0, 0); } while (0)
; #define PG8_LDA(dst, b, h) do { _Pragma("unroll") for (int m = 0; m < 4; ++m) _Pragma("unroll") for (int k = 0; k < 2; ++k) dst[m][k] = *(const PG8_LAS bf16x8*)(lds + PG8_SA(b, h) + aoff + m * 2048 + k * 1024); } while (0)
; #define PG8_LDB(dst, b, h) do { _Pragma("unroll") for (int n = 0; n < 2; ++n) _Pragma("unroll") for (int k = 0; k < 2; ++k) dst[n][k] = *(const PG8_LAS bf16x8*)(lds + PG8_SB(b, h) + boff + n * 2048 + k * 1024); } while (0)
; #define PG8_MMA(ai, bj, At, Bt) do { __builtin_amdgcn_s_setprio(1); _Pragma("unroll") for (int m = 0; m < 4; ++m) _Pragma("unroll") for (int n = 0; n < 2; ++n) _Pragma("unroll") for (int k = 0; k < 2; ++k) \
;         acc[ai][bj][m][n] = __builtin_amdgcn_mfma_f32_16x16x32_bf16(Bt[n][k], At[m][k], acc[ai][bj][m][n], 0, 0, 0); __builtin_amdgcn_s_setprio(0); } while (0)
; #define PG8_WAIT_V(n) asm volatile("s_waitcnt vmcnt(" #n ")" ::: "memory")
; #define PG8_WAIT_L(n) asm volatile("s_waitcnt lgkmcnt(" #n ")" ::: "memory")
; #define PG8_BAR __builtin_amdgcn_s_barrier()
; #define PG8_SCHED __builtin_amdgcn_sched_barrier(0)
; template <class Epi, class Sched, bool ALIGN_EPI = false, bool SP2 = false>
; __device__ __forceinline__ void gemm_phase(PG8_LAS unsigned char* lds, const Gemm g, const Sched& S, const Epi& E) {
;     ...
;             PG8_WAIT_V(8); PG8_WAIT_L(0); PG8_BAR; PG8_MMA(1, 0, At, B0); PG8_MMA(1, 1, At, B1); PG8_BAR; PG8_SCHED;
;             PG8_LDB(B0, 1, 0); PG8_LDB(B1, 1, 1); PG8_SCHED; PG8_LDA(At, 1, 0); PG8_STAGE(PG8_SA(0, 1), a2 + hstepA, voffA);
;             PG8_WAIT_V(8); PG8_WAIT_L(0); PG8_BAR; PG8_MMA(0, 0, At, B0); PG8_MMA(0, 1, At, B1); PG8_BAR; PG8_SCHED;
	s_setprio 1
	s_waitcnt lgkmcnt(0)
	v_mfma_f32_16x16x32_bf16 v[108:111], v[128:131], v[170:173], v[108:111]
	v_mfma_f32_16x16x32_bf16 v[76:79], v[142:145], v[170:173], v[76:79]
	v_mfma_f32_16x16x32_bf16 v[104:107], v[128:131], v[178:181], v[104:107]
	v_mfma_f32_16x16x32_bf16 v[68:71], v[142:145], v[178:181], v[68:71]
	v_mfma_f32_16x16x32_bf16 v[100:103], v[128:131], v[192:195], v[100:103]
	v_mfma_f32_16x16x32_bf16 v[60:63], v[142:145], v[192:195], v[60:63]
	v_mfma_f32_16x16x32_bf16 v[84:87], v[128:131], v[234:237], v[84:87]
	v_mfma_f32_16x16x32_bf16 v[52:55], v[142:145], v[234:237], v[52:55]
	v_mfma_f32_16x16x32_bf16 v[108:111], v[138:141], v[174:177], v[108:111]
	v_mfma_f32_16x16x32_bf16 v[76:79], v[150:153], v[174:177], v[76:79]
	v_mfma_f32_16x16x32_bf16 v[104:107], v[138:141], v[182:185], v[104:107]
	v_mfma_f32_16x16x32_bf16 v[68:71], v[150:153], v[182:185], v[68:71]
	v_mfma_f32_16x16x32_bf16 v[100:103], v[138:141], v[230:233], v[100:103]
	v_mfma_f32_16x16x32_bf16 v[60:63], v[150:153], v[230:233], v[60:63]
	v_mfma_f32_16x16x32_bf16 v[84:87], v[138:141], v[238:241], v[84:87]
	v_mfma_f32_16x16x32_bf16 v[52:55], v[150:153], v[238:241], v[52:55]
	s_setprio 0
	s_setprio 1
	v_mfma_f32_16x16x32_bf16 v[40:43], v[154:157], v[170:173], v[40:43]
	v_mfma_f32_16x16x32_bf16 v[12:15], v[162:165], v[170:173], v[12:15]
	v_mfma_f32_16x16x32_bf16 v[32:35], v[154:157], v[178:181], v[32:35]
	v_mfma_f32_16x16x32_bf16 v[8:11], v[162:165], v[178:181], v[8:11]
	v_mfma_f32_16x16x32_bf16 v[24:27], v[154:157], v[192:195], v[24:27]
	v_mfma_f32_16x16x32_bf16 v[4:7], v[162:165], v[192:195], v[4:7]
	v_mfma_f32_16x16x32_bf16 v[16:19], v[154:157], v[234:237], v[16:19]
	v_mfma_f32_16x16x32_bf16 v[0:3], v[162:165], v[234:237], v[0:3]
	v_mfma_f32_16x16x32_bf16 v[40:43], v[158:161], v[174:177], v[40:43]
	v_mfma_f32_16x16x32_bf16 v[12:15], v[166:169], v[174:177], v[12:15]
	v_mfma_f32_16x16x32_bf16 v[32:35], v[158:161], v[182:185], v[32:35]
	v_mfma_f32_16x16x32_bf16 v[8:11], v[166:169], v[182:185], v[8:11]
	v_mfma_f32_16x16x32_bf16 v[24:27], v[158:161], v[230:233], v[24:27]
	v_mfma_f32_16x16x32_bf16 v[4:7], v[166:169], v[230:233], v[4:7]
	v_mfma_f32_16x16x32_bf16 v[16:19], v[158:161], v[238:241], v[16:19]
	v_mfma_f32_16x16x32_bf16 v[0:3], v[166:169], v[238:241], v[0:3]
	s_setprio 0
	s_barrier
	v_add_u32_e32 v150, 0x18000, v148
	v_add_u32_e32 v166, 0x1c000, v148
	ds_read_b128 v[128:131], v150
	ds_read_b128 v[138:141], v150 offset:1024
	ds_read_b128 v[142:145], v150 offset:2048
	ds_read_b128 v[150:153], v150 offset:3072
	ds_read_b128 v[154:157], v166
	ds_read_b128 v[158:161], v166 offset:1024
	ds_read_b128 v[162:165], v166 offset:2048
	ds_read_b128 v[166:169], v166 offset:3072
	ds_read_b128 v[170:173], v149 offset:32768
	ds_read_b128 v[174:177], v149 offset:33792
	ds_read_b128 v[178:181], v149 offset:34816
	ds_read_b128 v[182:185], v149 offset:35840
	ds_read_b128 v[192:195], v149 offset:36864
	ds_read_b128 v[230:233], v149 offset:37888
	ds_read_b128 v[234:237], v149 offset:38912
	ds_read_b128 v[238:241], v149 offset:39936
	s_add_i32 s75, 0, 0x18000
	s_add_i32 s76, 0, 0x1c000
	s_add_u32 s28, s28, s44
	s_addc_u32 s29, s29, 0
	s_mov_b32 m0, s46
	v_lshl_add_u64 v[250:251], s[28:29], 0, v[188:189]
	global_load_lds_dwordx4 v[250:251], off
	s_mov_b32 m0, s47
	v_lshl_add_u64 v[250:251], s[28:29], 0, v[132:133]
	global_load_lds_dwordx4 v[250:251], off
	s_waitcnt vmcnt(8)
	s_waitcnt lgkmcnt(0)
	s_barrier
	s_setprio 1
	s_waitcnt lgkmcnt(0)
	v_mfma_f32_16x16x32_bf16 v[124:127], v[128:131], v[170:173], v[124:127]
	v_mfma_f32_16x16x32_bf16 v[96:99], v[142:145], v[170:173], v[96:99]
	v_mfma_f32_16x16x32_bf16 v[120:123], v[128:131], v[178:181], v[120:123]
	v_mfma_f32_16x16x32_bf16 v[92:95], v[142:145], v[178:181], v[92:95]
	v_mfma_f32_16x16x32_bf16 v[116:119], v[128:131], v[192:195], v[116:119]
	v_mfma_f32_16x16x32_bf16 v[88:91], v[142:145], v[192:195], v[88:91]
	v_mfma_f32_16x16x32_bf16 v[112:115], v[128:131], v[234:237], v[112:115]
	v_mfma_f32_16x16x32_bf16 v[80:83], v[142:145], v[234:237], v[80:83]
	v_mfma_f32_16x16x32_bf16 v[124:127], v[138:141], v[174:177], v[124:127]
	v_mfma_f32_16x16x32_bf16 v[96:99], v[150:153], v[174:177], v[96:99]
	v_mfma_f32_16x16x32_bf16 v[120:123], v[138:141], v[182:185], v[120:123]
	v_mfma_f32_16x16x32_bf16 v[92:95], v[150:153], v[182:185], v[92:95]
	v_mfma_f32_16x16x32_bf16 v[116:119], v[138:141], v[230:233], v[116:119]
	v_mfma_f32_16x16x32_bf16 v[88:91], v[150:153], v[230:233], v[88:91]
	v_mfma_f32_16x16x32_bf16 v[112:115], v[138:141], v[238:241], v[112:115]
	v_mfma_f32_16x16x32_bf16 v[80:83], v[150:153], v[238:241], v[80:83]
	s_setprio 0
	s_setprio 1
	v_mfma_f32_16x16x32_bf16 v[72:75], v[154:157], v[170:173], v[72:75]
	v_mfma_f32_16x16x32_bf16 v[44:47], v[162:165], v[170:173], v[44:47]
	v_mfma_f32_16x16x32_bf16 v[64:67], v[154:157], v[178:181], v[64:67]
	v_mfma_f32_16x16x32_bf16 v[36:39], v[162:165], v[178:181], v[36:39]
	v_mfma_f32_16x16x32_bf16 v[56:59], v[154:157], v[192:195], v[56:59]
	v_mfma_f32_16x16x32_bf16 v[28:31], v[162:165], v[192:195], v[28:31]
	v_mfma_f32_16x16x32_bf16 v[48:51], v[154:157], v[234:237], v[48:51]
	v_mfma_f32_16x16x32_bf16 v[20:23], v[162:165], v[234:237], v[20:23]
	v_mfma_f32_16x16x32_bf16 v[72:75], v[158:161], v[174:177], v[72:75]
	v_mfma_f32_16x16x32_bf16 v[44:47], v[166:169], v[174:177], v[44:47]
	v_mfma_f32_16x16x32_bf16 v[64:67], v[158:161], v[182:185], v[64:67]
	v_mfma_f32_16x16x32_bf16 v[36:39], v[166:169], v[182:185], v[36:39]
	v_mfma_f32_16x16x32_bf16 v[56:59], v[158:161], v[230:233], v[56:59]
	v_mfma_f32_16x16x32_bf16 v[28:31], v[166:169], v[230:233], v[28:31]
	v_mfma_f32_16x16x32_bf16 v[48:51], v[158:161], v[238:241], v[48:51]
	v_mfma_f32_16x16x32_bf16 v[20:23], v[166:169], v[238:241], v[20:23]
	s_setprio 0
	s_barrier
; #define PG8_STAGE(bufoff, gbase, voff) do { _Pragma("unroll") for (int _i = 0; _i < 2; ++_i) \
;         __builtin_amdgcn_global_load_lds((const unsigned*)((const char*)(gbase) + (voff)[_i]), (PG8_LAS unsigned*)(lds + (bufoff) + ldsw + _i * 8192), 16, 0, 0); } while (0)
; #define PG8_LDA(dst, b, h) do { _Pragma("unroll") for (int m = 0; m < 4; ++m) _Pragma("unroll") for (int k = 0; k < 2; ++k) dst[m][k] = *(const PG8_LAS bf16x8*)(lds + PG8_SA(b, h) + aoff + m * 2048 + k * 1024); } while (0)
; #define PG8_MMA(ai, bj, At, Bt) do { __builtin_amdgcn_s_setprio(1); _Pragma("unroll") for (int m = 0; m < 4; ++m) _Pragma("unroll") for (int n = 0; n < 2; ++n) _Pragma("unroll") for (int k = 0; k < 2; ++k) \
;         acc[ai][bj][m][n] = __builtin_amdgcn_mfma_f32_16x16x32_bf16(Bt[n][k], At[m][k], acc[ai][bj][m][n], 0, 0, 0); __builtin_amdgcn_s_setprio(0); } while (0)
; #define PG8_WAIT_V(n) asm volatile("s_waitcnt vmcnt(" #n ")" ::: "memory")
; #define PG8_WAIT_L(n) asm volatile("s_waitcnt lgkmcnt(" #n ")" ::: "memory")
; #define PG8_BAR __builtin_amdgcn_s_barrier()
; #define PG8_SCHED __builtin_amdgcn_sched_barrier(0)
; template <class Epi, class Sched, bool ALIGN_EPI = false, bool SP2 = false>
; __device__ __forceinline__ void gemm_phase(PG8_LAS unsigned char* lds, const Gemm g, const Sched& S, const Epi& E) {
;     ...
;         for (int t = 0; t < nt; t += 2) {
;     ...
;             PG8_LDA(At, 1, 1); PG8_STAGE(PG8_SB(1, 0), b3, voffB); PG8_STAGE(PG8_SB(1, 1), b3 + hstepB, voffB); PG8_STAGE(PG8_SA(1, 0), a3, voffA);
;             PG8_WAIT_V(8); PG8_WAIT_L(0); PG8_BAR; PG8_MMA(1, 0, At, B0); PG8_MMA(1, 1, At, B1); PG8_BAR; PG8_SCHED;
	ds_read_b128 v[170:173], v149 offset:49152
	ds_read_b128 v[174:177], v149 offset:50176
	ds_read_b128 v[178:181], v149 offset:51200
	ds_read_b128 v[182:185], v149 offset:52224
	ds_read_b128 v[192:195], v149 offset:53248
	ds_read_b128 v[230:233], v149 offset:54272
	ds_read_b128 v[234:237], v149 offset:55296
	ds_read_b128 v[238:241], v149 offset:56320
	s_add_i32 s28, s75, s30
	v_lshl_add_u64 v[186:187], v[186:187], 0, s[94:95]
	s_mov_b32 m0, s28
	global_load_lds_dwordx4 v[186:187], off
	v_lshl_add_u64 v[186:187], v[196:197], 0, s[94:95]
	s_add_i32 m0, s28, 0x2000
	s_add_i32 s28, s76, s30
	global_load_lds_dwordx4 v[186:187], off
	s_mov_b32 m0, s28
	v_lshl_add_u64 v[186:187], v[242:243], 0, s[94:95]
	global_load_lds_dwordx4 v[186:187], off
	s_add_i32 m0, s28, 0x2000
	v_lshl_add_u64 v[186:187], v[244:245], 0, s[94:95]
	global_load_lds_dwordx4 v[186:187], off
	s_mov_b32 m0, s62
	v_lshl_add_u64 v[186:187], v[246:247], 0, s[94:95]
	global_load_lds_dwordx4 v[186:187], off
	s_mov_b32 m0, s63
	v_lshl_add_u64 v[186:187], v[248:249], 0, s[94:95]
	global_load_lds_dwordx4 v[186:187], off
	s_waitcnt vmcnt(8)
	s_waitcnt lgkmcnt(0)
	s_barrier
	s_setprio 1
	s_waitcnt lgkmcnt(0)
	v_mfma_f32_16x16x32_bf16 v[108:111], v[128:131], v[170:173], v[108:111]
	v_mfma_f32_16x16x32_bf16 v[76:79], v[142:145], v[170:173], v[76:79]
	v_mfma_f32_16x16x32_bf16 v[104:107], v[128:131], v[178:181], v[104:107]
	v_mfma_f32_16x16x32_bf16 v[68:71], v[142:145], v[178:181], v[68:71]
	v_mfma_f32_16x16x32_bf16 v[100:103], v[128:131], v[192:195], v[100:103]
	v_mfma_f32_16x16x32_bf16 v[60:63], v[142:145], v[192:195], v[60:63]
	v_mfma_f32_16x16x32_bf16 v[84:87], v[128:131], v[234:237], v[84:87]
	v_mfma_f32_16x16x32_bf16 v[52:55], v[142:145], v[234:237], v[52:55]
	v_mfma_f32_16x16x32_bf16 v[108:111], v[138:141], v[174:177], v[108:111]
	v_mfma_f32_16x16x32_bf16 v[76:79], v[150:153], v[174:177], v[76:79]
	v_mfma_f32_16x16x32_bf16 v[104:107], v[138:141], v[182:185], v[104:107]
	v_mfma_f32_16x16x32_bf16 v[68:71], v[150:153], v[182:185], v[68:71]
	v_mfma_f32_16x16x32_bf16 v[100:103], v[138:141], v[230:233], v[100:103]
	v_mfma_f32_16x16x32_bf16 v[60:63], v[150:153], v[230:233], v[60:63]
	v_mfma_f32_16x16x32_bf16 v[84:87], v[138:141], v[238:241], v[84:87]
	v_mfma_f32_16x16x32_bf16 v[52:55], v[150:153], v[238:241], v[52:55]
	s_setprio 0
	s_setprio 1
	v_mfma_f32_16x16x32_bf16 v[40:43], v[154:157], v[170:173], v[40:43]
	v_mfma_f32_16x16x32_bf16 v[12:15], v[162:165], v[170:173], v[12:15]
	v_mfma_f32_16x16x32_bf16 v[32:35], v[154:157], v[178:181], v[32:35]
	v_mfma_f32_16x16x32_bf16 v[8:11], v[162:165], v[178:181], v[8:11]
	v_mfma_f32_16x16x32_bf16 v[24:27], v[154:157], v[192:195], v[24:27]
	v_mfma_f32_16x16x32_bf16 v[4:7], v[162:165], v[192:195], v[4:7]
	v_mfma_f32_16x16x32_bf16 v[16:19], v[154:157], v[234:237], v[16:19]
	v_mfma_f32_16x16x32_bf16 v[0:3], v[162:165], v[234:237], v[0:3]
	v_mfma_f32_16x16x32_bf16 v[40:43], v[158:161], v[174:177], v[40:43]
	v_mfma_f32_16x16x32_bf16 v[12:15], v[166:169], v[174:177], v[12:15]
	v_mfma_f32_16x16x32_bf16 v[32:35], v[158:161], v[182:185], v[32:35]
	v_mfma_f32_16x16x32_bf16 v[8:11], v[166:169], v[182:185], v[8:11]
	v_mfma_f32_16x16x32_bf16 v[24:27], v[158:161], v[230:233], v[24:27]
	v_mfma_f32_16x16x32_bf16 v[4:7], v[166:169], v[230:233], v[4:7]
	v_mfma_f32_16x16x32_bf16 v[16:19], v[158:161], v[238:241], v[16:19]
	v_mfma_f32_16x16x32_bf16 v[0:3], v[166:169], v[238:241], v[0:3]
	s_setprio 0
	s_barrier
	s_add_u32 s26, s26, 0x100
	s_addc_u32 s27, s27, 0
	s_add_u32 s72, s72, 0x100
	s_addc_u32 s73, s73, 0
	s_cmp_ge_u32 s74, s52
	s_mov_b32 s28, s74
	s_cbranch_scc0 .LBB0_1642
	s_and_b64 vcc, exec, s[14:15]
	s_cbranch_vccz .LBB0_1645
	s_barrier

; #define PG8_STAGE(bufoff, gbase, voff) do { _Pragma("unroll") for (int _i = 0; _i < 2; ++_i) \
;         __builtin_amdgcn_global_load_lds((const unsigned*)((const char*)(gbase) + (voff)[_i]), (PG8_LAS unsigned*)(lds + (bufoff) + ldsw + _i * 8192), 16, 0, 0); } while (0)
; #define PG8_LDA(dst, b, h) do { _Pragma("unroll") for (int m = 0; m < 4; ++m) _Pragma("unroll") for (int k = 0; k < 2; ++k) dst[m][k] = *(const PG8_LAS bf16x8*)(lds + PG8_SA(b, h) + aoff + m * 2048 + k * 1024); } while (0)
; #define PG8_LDB(dst, b, h) do { _Pragma("unroll") for (int n = 0; n < 2; ++n) _Pragma("unroll") for (int k = 0; k < 2; ++k) dst[n][k] = *(const PG8_LAS bf16x8*)(lds + PG8_SB(b, h) + boff + n * 2048 + k * 1024); } while (0)
; #define PG8_MMA(ai, bj, At, Bt) do { __builtin_amdgcn_s_setprio(1); _Pragma("unroll") for (int m = 0; m < 4; ++m) _Pragma("unroll") for (int n = 0; n < 2; ++n) _Pragma("unroll") for (int k = 0; k < 2; ++k) \
;         acc[ai][bj][m][n] = __builtin_amdgcn_mfma_f32_16x16x32_bf16(Bt[n][k], At[m][k], acc[ai][bj][m][n], 0, 0, 0); __builtin_amdgcn_s_setprio(0); } while (0)
; #define PG8_WAIT_V(n) asm volatile("s_waitcnt vmcnt(" #n ")" ::: "memory")
; #define PG8_WAIT_L(n) asm volatile("s_waitcnt lgkmcnt(" #n ")" ::: "memory")
; #define PG8_BAR __builtin_amdgcn_s_barrier()
; #define PG8_SCHED __builtin_amdgcn_sched_barrier(0)
; template <class Epi, class Sched, bool ALIGN_EPI = false, bool SP2 = false>
; __device__ __forceinline__ void gemm_phase(PG8_LAS unsigned char* lds, const Gemm g, const Sched& S, const Epi& E) {
;     ...
;             const bool last = (t == nt - 2);
;             const char* a1 = cA + (size_t)(t + 1) * kstep;
;             const char* a2 = last ? nA : cA + (size_t)(t + 2) * kstep; const char* b2 = last ? nB : cB + (size_t)(t + 2) * kstep;
;             const char* a3 = a2 + kstep; const char* b3 = b2 + kstep;
;             if (last && has_next) S.a_ready(nxt);
;             if constexpr (SP2) {
;             PG8_LDB(B0, 0, 0); PG8_LDB(B1, 0, 1); PG8_SCHED; PG8_LDA(At, 0, 0); PG8_STAGE(PG8_SA(1, 1), a1 + hstepA, voffA);
;             PG8_WAIT_V(8); PG8_WAIT_L(0); PG8_BAR; PG8_MMA(0, 0, At, B0); PG8_MMA(0, 1, At, B1); PG8_BAR; PG8_SCHED;
;             PG8_LDA(At, 0, 1); PG8_STAGE(PG8_SB(0, 0), b2, voffB); PG8_STAGE(PG8_SB(0, 1), b2 + hstepB, voffB); PG8_STAGE(PG8_SA(0, 0), a2, voffA);
.LBB0_1800:
	v_add_u32_e32 v140, 0x10000, v229
	v_add_u32_e32 v156, 0x14000, v229
	ds_read_b128 v[128:131], v140
	ds_read_b128 v[132:135], v140 offset:1024
	ds_read_b128 v[136:139], v140 offset:2048
	ds_read_b128 v[140:143], v140 offset:3072
	ds_read_b128 v[144:147], v156
	ds_read_b128 v[148:151], v156 offset:1024
	ds_read_b128 v[152:155], v156 offset:2048
	ds_read_b128 v[156:159], v156 offset:3072
	ds_read_b128 v[160:163], v230
	ds_read_b128 v[164:167], v230 offset:1024
	ds_read_b128 v[178:181], v230 offset:2048
	ds_read_b128 v[182:185], v230 offset:3072
	ds_read_b128 v[192:195], v230 offset:4096
	ds_read_b128 v[232:235], v230 offset:5120
	ds_read_b128 v[236:239], v230 offset:6144
	ds_read_b128 v[240:243], v230 offset:7168
	s_add_u32 s10, s8, 0xfffc0080
	s_addc_u32 s11, s9, -1
	s_add_i32 s71, 0, 0x10000
	s_cmp_eq_u32 s70, 12
	s_cselect_b32 s45, s13, s11
	s_cselect_b32 s44, s15, s10
	s_cselect_b32 s11, s35, s47
	s_cselect_b32 s10, s37, s46
	s_add_i32 s74, 0, 0x14000
	v_lshl_add_u64 v[186:187], s[8:9], 0, v[174:175]
	s_add_i32 m0, s54, 0xc000
	global_load_lds_dwordx4 v[186:187], off
	s_add_i32 m0, s54, 0xe000
	v_lshl_add_u64 v[186:187], s[8:9], 0, v[176:177]
	global_load_lds_dwordx4 v[186:187], off
	s_waitcnt vmcnt(8)
	s_waitcnt lgkmcnt(0)
	s_barrier
	s_setprio 1
	s_waitcnt lgkmcnt(0)
	v_mfma_f32_16x16x32_bf16 v[124:127], v[128:131], v[160:163], v[124:127]
	v_mfma_f32_16x16x32_bf16 v[60:63], v[136:139], v[160:163], v[60:63]
	v_mfma_f32_16x16x32_bf16 v[120:123], v[128:131], v[178:181], v[120:123]
	v_mfma_f32_16x16x32_bf16 v[56:59], v[136:139], v[178:181], v[56:59]
	v_mfma_f32_16x16x32_bf16 v[108:111], v[128:131], v[192:195], v[108:111]
	v_mfma_f32_16x16x32_bf16 v[44:47], v[136:139], v[192:195], v[44:47]
	v_mfma_f32_16x16x32_bf16 v[100:103], v[128:131], v[236:239], v[100:103]
	v_mfma_f32_16x16x32_bf16 v[36:39], v[136:139], v[236:239], v[36:39]
	v_mfma_f32_16x16x32_bf16 v[124:127], v[132:135], v[164:167], v[124:127]
	v_mfma_f32_16x16x32_bf16 v[60:63], v[140:143], v[164:167], v[60:63]
	v_mfma_f32_16x16x32_bf16 v[120:123], v[132:135], v[182:185], v[120:123]
	v_mfma_f32_16x16x32_bf16 v[56:59], v[140:143], v[182:185], v[56:59]
	v_mfma_f32_16x16x32_bf16 v[108:111], v[132:135], v[232:235], v[108:111]
	v_mfma_f32_16x16x32_bf16 v[44:47], v[140:143], v[232:235], v[44:47]
	v_mfma_f32_16x16x32_bf16 v[100:103], v[132:135], v[240:243], v[100:103]
	v_mfma_f32_16x16x32_bf16 v[36:39], v[140:143], v[240:243], v[36:39]
	s_setprio 0
	s_setprio 1
	v_mfma_f32_16x16x32_bf16 v[116:119], v[144:147], v[160:163], v[116:119]
	v_mfma_f32_16x16x32_bf16 v[52:55], v[152:155], v[160:163], v[52:55]
	v_mfma_f32_16x16x32_bf16 v[112:115], v[144:147], v[178:181], v[112:115]
	v_mfma_f32_16x16x32_bf16 v[48:51], v[152:155], v[178:181], v[48:51]
	v_mfma_f32_16x16x32_bf16 v[104:107], v[144:147], v[192:195], v[104:107]
	v_mfma_f32_16x16x32_bf16 v[40:43], v[152:155], v[192:195], v[40:43]
	v_mfma_f32_16x16x32_bf16 v[96:99], v[144:147], v[236:239], v[96:99]
	v_mfma_f32_16x16x32_bf16 v[32:35], v[152:155], v[236:239], v[32:35]
	v_mfma_f32_16x16x32_bf16 v[116:119], v[148:151], v[164:167], v[116:119]
	v_mfma_f32_16x16x32_bf16 v[52:55], v[156:159], v[164:167], v[52:55]
	v_mfma_f32_16x16x32_bf16 v[112:115], v[148:151], v[182:185], v[112:115]
	v_mfma_f32_16x16x32_bf16 v[48:51], v[156:159], v[182:185], v[48:51]
	v_mfma_f32_16x16x32_bf16 v[104:107], v[148:151], v[232:235], v[104:107]
	v_mfma_f32_16x16x32_bf16 v[40:43], v[156:159], v[232:235], v[40:43]
	v_mfma_f32_16x16x32_bf16 v[96:99], v[148:151], v[240:243], v[96:99]
	v_mfma_f32_16x16x32_bf16 v[32:35], v[156:159], v[240:243], v[32:35]
	s_setprio 0
	s_barrier
	ds_read_b128 v[160:163], v230 offset:16384
	ds_read_b128 v[164:167], v230 offset:17408
	ds_read_b128 v[178:181], v230 offset:18432
	ds_read_b128 v[182:185], v230 offset:19456
	ds_read_b128 v[192:195], v230 offset:20480
	ds_read_b128 v[232:235], v230 offset:21504
	ds_read_b128 v[236:239], v230 offset:22528
	ds_read_b128 v[240:243], v230 offset:23552
	s_add_i32 s71, s71, s53
	v_lshl_add_u64 v[186:187], s[10:11], 0, v[188:189]
	s_mov_b32 m0, s71
	global_load_lds_dwordx4 v[186:187], off
	s_add_i32 m0, s71, 0x2000
	s_add_u32 s72, s10, 0x40000
	v_lshl_add_u64 v[244:245], s[10:11], 0, v[172:173]
	s_addc_u32 s73, s11, 0
	s_add_i32 s71, s74, s53
	global_load_lds_dwordx4 v[244:245], off
	v_lshl_add_u64 v[246:247], s[72:73], 0, v[188:189]
	s_mov_b32 m0, s71
	v_lshl_add_u64 v[248:249], s[44:45], 0, v[170:171]
	global_load_lds_dwordx4 v[246:247], off
	s_add_i32 m0, s71, 0x2000
	v_lshl_add_u64 v[246:247], s[72:73], 0, v[172:173]
	global_load_lds_dwordx4 v[246:247], off
	s_mov_b32 m0, s54
	v_lshl_add_u64 v[246:247], s[44:45], 0, v[168:169]
	global_load_lds_dwordx4 v[246:247], off
	s_mov_b32 m0, s55
	s_nop 0
	global_load_lds_dwordx4 v[248:249], off
	s_waitcnt vmcnt(8)
	s_waitcnt lgkmcnt(0)
	s_barrier
; #define PG8_STAGE(bufoff, gbase, voff) do { _Pragma("unroll") for (int _i = 0; _i < 2; ++_i) \
;         __builtin_amdgcn_global_load_lds((const unsigned*)((const char*)(gbase) + (voff)[_i]), (PG8_LAS unsigned*)(lds + (bufoff) + ldsw + _i * 8192), 16, 0, 0); } while (0)
; #define PG8_LDA(dst, b, h) do { _Pragma("unroll") for (int m = 0; m < 4; ++m) _Pragma("unroll") for (int k = 0; k < 2; ++k) dst[m][k] = *(const PG8_LAS bf16x8*)(lds + PG8_SA(b, h) + aoff + m * 2048 + k * 1024); } while (0)
; #define PG8_LDB(dst, b, h) do { _Pragma("unroll") for (int n = 0; n < 2; ++n) _Pragma("unroll") for (int k = 0; k < 2; ++k) dst[n][k] = *(const PG8_LAS bf16x8*)(lds + PG8_SB(b, h) + boff + n * 2048 + k * 1024); } while (0)
; #define PG8_MMA(ai, bj, At, Bt) do { __builtin_amdgcn_s_setprio(1); _Pragma("unroll") for (int m = 0; m < 4; ++m) _Pragma("unroll") for (int n = 0; n < 2; ++n) _Pragma("unroll") for (int k = 0; k < 2; ++k) \
;         acc[ai][bj][m][n] = __builtin_amdgcn_mfma_f32_16x16x32_bf16(Bt[n][k], At[m][k], acc[ai][bj][m][n], 0, 0, 0); __builtin_amdgcn_s_setprio(0); } while (0)
; #define PG8_WAIT_V(n) asm volatile("s_waitcnt vmcnt(" #n ")" ::: "memory")
; #define PG8_WAIT_L(n) asm volatile("s_waitcnt lgkmcnt(" #n ")" ::: "memory")
; #define PG8_BAR __builtin_amdgcn_s_barrier()
; #define PG8_SCHED __builtin_amdgcn_sched_barrier(0)
; template <class Epi, class Sched, bool ALIGN_EPI = false, bool SP2 = false>
; __device__ __forceinline__ void gemm_phase(PG8_LAS unsigned char* lds, const Gemm g, const Sched& S, const Epi& E) {
;     ...
;             PG8_WAIT_V(8); PG8_WAIT_L(0); PG8_BAR; PG8_MMA(1, 0, At, B0); PG8_MMA(1, 1, At, B1); PG8_BAR; PG8_SCHED;
;             PG8_LDB(B0, 1, 0); PG8_LDB(B1, 1, 1); PG8_SCHED; PG8_LDA(At, 1, 0); PG8_STAGE(PG8_SA(0, 1), a2 + hstepA, voffA);
;             PG8_WAIT_V(8); PG8_WAIT_L(0); PG8_BAR; PG8_MMA(0, 0, At, B0); PG8_MMA(0, 1, At, B1); PG8_BAR; PG8_SCHED;
	s_setprio 1
	s_waitcnt lgkmcnt(0)
	v_mfma_f32_16x16x32_bf16 v[92:95], v[128:131], v[160:163], v[92:95]
	v_mfma_f32_16x16x32_bf16 v[28:31], v[136:139], v[160:163], v[28:31]
	v_mfma_f32_16x16x32_bf16 v[88:91], v[128:131], v[178:181], v[88:91]
	v_mfma_f32_16x16x32_bf16 v[24:27], v[136:139], v[178:181], v[24:27]
	v_mfma_f32_16x16x32_bf16 v[76:79], v[128:131], v[192:195], v[76:79]
	v_mfma_f32_16x16x32_bf16 v[12:15], v[136:139], v[192:195], v[12:15]
	v_mfma_f32_16x16x32_bf16 v[68:71], v[128:131], v[236:239], v[68:71]
	v_mfma_f32_16x16x32_bf16 v[4:7], v[136:139], v[236:239], v[4:7]
	v_mfma_f32_16x16x32_bf16 v[92:95], v[132:135], v[164:167], v[92:95]
	v_mfma_f32_16x16x32_bf16 v[28:31], v[140:143], v[164:167], v[28:31]
	v_mfma_f32_16x16x32_bf16 v[88:91], v[132:135], v[182:185], v[88:91]
	v_mfma_f32_16x16x32_bf16 v[24:27], v[140:143], v[182:185], v[24:27]
	v_mfma_f32_16x16x32_bf16 v[76:79], v[132:135], v[232:235], v[76:79]
	v_mfma_f32_16x16x32_bf16 v[12:15], v[140:143], v[232:235], v[12:15]
	v_mfma_f32_16x16x32_bf16 v[68:71], v[132:135], v[240:243], v[68:71]
	v_mfma_f32_16x16x32_bf16 v[4:7], v[140:143], v[240:243], v[4:7]
	s_setprio 0
	s_setprio 1
	v_mfma_f32_16x16x32_bf16 v[84:87], v[144:147], v[160:163], v[84:87]
	v_mfma_f32_16x16x32_bf16 v[20:23], v[152:155], v[160:163], v[20:23]
	v_mfma_f32_16x16x32_bf16 v[80:83], v[144:147], v[178:181], v[80:83]
	v_mfma_f32_16x16x32_bf16 v[16:19], v[152:155], v[178:181], v[16:19]
	v_mfma_f32_16x16x32_bf16 v[72:75], v[144:147], v[192:195], v[72:75]
	v_mfma_f32_16x16x32_bf16 v[8:11], v[152:155], v[192:195], v[8:11]
	v_mfma_f32_16x16x32_bf16 v[64:67], v[144:147], v[236:239], v[64:67]
	v_mfma_f32_16x16x32_bf16 v[0:3], v[152:155], v[236:239], v[0:3]
	v_mfma_f32_16x16x32_bf16 v[84:87], v[148:151], v[164:167], v[84:87]
	v_mfma_f32_16x16x32_bf16 v[20:23], v[156:159], v[164:167], v[20:23]
	v_mfma_f32_16x16x32_bf16 v[80:83], v[148:151], v[182:185], v[80:83]
	v_mfma_f32_16x16x32_bf16 v[16:19], v[156:159], v[182:185], v[16:19]
	v_mfma_f32_16x16x32_bf16 v[72:75], v[148:151], v[232:235], v[72:75]
	v_mfma_f32_16x16x32_bf16 v[8:11], v[156:159], v[232:235], v[8:11]
	v_mfma_f32_16x16x32_bf16 v[64:67], v[148:151], v[240:243], v[64:67]
	v_mfma_f32_16x16x32_bf16 v[0:3], v[156:159], v[240:243], v[0:3]
	s_setprio 0
	s_barrier
	v_add_u32_e32 v140, 0x18000, v229
	v_add_u32_e32 v156, 0x1c000, v229
	ds_read_b128 v[128:131], v140
	ds_read_b128 v[132:135], v140 offset:1024
	ds_read_b128 v[136:139], v140 offset:2048
	ds_read_b128 v[140:143], v140 offset:3072
	ds_read_b128 v[144:147], v156
	ds_read_b128 v[148:151], v156 offset:1024
	ds_read_b128 v[152:155], v156 offset:2048
	ds_read_b128 v[156:159], v156 offset:3072
	ds_read_b128 v[160:163], v230 offset:32768
	ds_read_b128 v[164:167], v230 offset:33792
	ds_read_b128 v[178:181], v230 offset:34816
	ds_read_b128 v[182:185], v230 offset:35840
	ds_read_b128 v[192:195], v230 offset:36864
	ds_read_b128 v[232:235], v230 offset:37888
	ds_read_b128 v[236:239], v230 offset:38912
	ds_read_b128 v[240:243], v230 offset:39936
	s_add_i32 s71, 0, 0x18000
	s_add_i32 s72, 0, 0x1c000
	s_add_u32 s44, s44, 0x40000
	s_addc_u32 s45, s45, 0
	s_mov_b32 m0, s56
	v_lshl_add_u64 v[250:251], s[44:45], 0, v[168:169]
	global_load_lds_dwordx4 v[250:251], off
	s_mov_b32 m0, s57
	v_lshl_add_u64 v[250:251], s[44:45], 0, v[170:171]
	global_load_lds_dwordx4 v[250:251], off
	s_waitcnt vmcnt(8)
	s_waitcnt lgkmcnt(0)
	s_barrier
	s_setprio 1
	s_waitcnt lgkmcnt(0)
	v_mfma_f32_16x16x32_bf16 v[124:127], v[128:131], v[160:163], v[124:127]
	v_mfma_f32_16x16x32_bf16 v[60:63], v[136:139], v[160:163], v[60:63]
	v_mfma_f32_16x16x32_bf16 v[120:123], v[128:131], v[178:181], v[120:123]
	v_mfma_f32_16x16x32_bf16 v[56:59], v[136:139], v[178:181], v[56:59]
	v_mfma_f32_16x16x32_bf16 v[108:111], v[128:131], v[192:195], v[108:111]
	v_mfma_f32_16x16x32_bf16 v[44:47], v[136:139], v[192:195], v[44:47]
	v_mfma_f32_16x16x32_bf16 v[100:103], v[128:131], v[236:239], v[100:103]
	v_mfma_f32_16x16x32_bf16 v[36:39], v[136:139], v[236:239], v[36:39]
	v_mfma_f32_16x16x32_bf16 v[124:127], v[132:135], v[164:167], v[124:127]
	v_mfma_f32_16x16x32_bf16 v[60:63], v[140:143], v[164:167], v[60:63]
	v_mfma_f32_16x16x32_bf16 v[120:123], v[132:135], v[182:185], v[120:123]
	v_mfma_f32_16x16x32_bf16 v[56:59], v[140:143], v[182:185], v[56:59]
	v_mfma_f32_16x16x32_bf16 v[108:111], v[132:135], v[232:235], v[108:111]
	v_mfma_f32_16x16x32_bf16 v[44:47], v[140:143], v[232:235], v[44:47]
	v_mfma_f32_16x16x32_bf16 v[100:103], v[132:135], v[240:243], v[100:103]
	v_mfma_f32_16x16x32_bf16 v[36:39], v[140:143], v[240:243], v[36:39]
	s_setprio 0
	s_setprio 1
	v_mfma_f32_16x16x32_bf16 v[116:119], v[144:147], v[160:163], v[116:119]
	v_mfma_f32_16x16x32_bf16 v[52:55], v[152:155], v[160:163], v[52:55]
	v_mfma_f32_16x16x32_bf16 v[112:115], v[144:147], v[178:181], v[112:115]
	v_mfma_f32_16x16x32_bf16 v[48:51], v[152:155], v[178:181], v[48:51]
	v_mfma_f32_16x16x32_bf16 v[104:107], v[144:147], v[192:195], v[104:107]
	v_mfma_f32_16x16x32_bf16 v[40:43], v[152:155], v[192:195], v[40:43]
	v_mfma_f32_16x16x32_bf16 v[96:99], v[144:147], v[236:239], v[96:99]
	v_mfma_f32_16x16x32_bf16 v[32:35], v[152:155], v[236:239], v[32:35]
	v_mfma_f32_16x16x32_bf16 v[116:119], v[148:151], v[164:167], v[116:119]
	v_mfma_f32_16x16x32_bf16 v[52:55], v[156:159], v[164:167], v[52:55]
	v_mfma_f32_16x16x32_bf16 v[112:115], v[148:151], v[182:185], v[112:115]
	v_mfma_f32_16x16x32_bf16 v[48:51], v[156:159], v[182:185], v[48:51]
	v_mfma_f32_16x16x32_bf16 v[104:107], v[148:151], v[232:235], v[104:107]
	v_mfma_f32_16x16x32_bf16 v[40:43], v[156:159], v[232:235], v[40:43]
	v_mfma_f32_16x16x32_bf16 v[96:99], v[148:151], v[240:243], v[96:99]
	v_mfma_f32_16x16x32_bf16 v[32:35], v[156:159], v[240:243], v[32:35]
	s_setprio 0
	s_barrier
; #define PG8_STAGE(bufoff, gbase, voff) do { _Pragma("unroll") for (int _i = 0; _i < 2; ++_i) \
;         __builtin_amdgcn_global_load_lds((const unsigned*)((const char*)(gbase) + (voff)[_i]), (PG8_LAS unsigned*)(lds + (bufoff) + ldsw + _i * 8192), 16, 0, 0); } while (0)
; #define PG8_LDA(dst, b, h) do { _Pragma("unroll") for (int m = 0; m < 4; ++m) _Pragma("unroll") for (int k = 0; k < 2; ++k) dst[m][k] = *(const PG8_LAS bf16x8*)(lds + PG8_SA(b, h) + aoff + m * 2048 + k * 1024); } while (0)
; #define PG8_MMA(ai, bj, At, Bt) do { __builtin_amdgcn_s_setprio(1); _Pragma("unroll") for (int m = 0; m < 4; ++m) _Pragma("unroll") for (int n = 0; n < 2; ++n) _Pragma("unroll") for (int k = 0; k < 2; ++k) \
;         acc[ai][bj][m][n] = __builtin_amdgcn_mfma_f32_16x16x32_bf16(Bt[n][k], At[m][k], acc[ai][bj][m][n], 0, 0, 0); __builtin_amdgcn_s_setprio(0); } while (0)
; #define PG8_WAIT_V(n) asm volatile("s_waitcnt vmcnt(" #n ")" ::: "memory")
; #define PG8_WAIT_L(n) asm volatile("s_waitcnt lgkmcnt(" #n ")" ::: "memory")
; #define PG8_BAR __builtin_amdgcn_s_barrier()
; #define PG8_SCHED __builtin_amdgcn_sched_barrier(0)
; template <class Epi, class Sched, bool ALIGN_EPI = false, bool SP2 = false>
; __device__ __forceinline__ void gemm_phase(PG8_LAS unsigned char* lds, const Gemm g, const Sched& S, const Epi& E) {
;     ...
;         for (int t = 0; t < nt; t += 2) {
;     ...
;             PG8_LDA(At, 1, 1); PG8_STAGE(PG8_SB(1, 0), b3, voffB); PG8_STAGE(PG8_SB(1, 1), b3 + hstepB, voffB); PG8_STAGE(PG8_SA(1, 0), a3, voffA);
;             PG8_WAIT_V(8); PG8_WAIT_L(0); PG8_BAR; PG8_MMA(1, 0, At, B0); PG8_MMA(1, 1, At, B1); PG8_BAR; PG8_SCHED;
	ds_read_b128 v[160:163], v230 offset:49152
	ds_read_b128 v[164:167], v230 offset:50176
	ds_read_b128 v[178:181], v230 offset:51200
	ds_read_b128 v[182:185], v230 offset:52224
	ds_read_b128 v[192:195], v230 offset:53248
	ds_read_b128 v[232:235], v230 offset:54272
	ds_read_b128 v[236:239], v230 offset:55296
	ds_read_b128 v[240:243], v230 offset:56320
	s_add_i32 s44, s71, s53
	v_lshl_add_u64 v[186:187], v[186:187], 0, s[94:95]
	s_mov_b32 m0, s44
	global_load_lds_dwordx4 v[186:187], off
	s_add_i32 m0, s44, 0x2000
	s_add_u32 s10, s10, 0x40080
	v_lshl_add_u64 v[186:187], v[244:245], 0, s[94:95]
	s_addc_u32 s11, s11, 0
	s_add_i32 s44, s72, s53
	global_load_lds_dwordx4 v[186:187], off
	s_mov_b32 m0, s44
	v_lshl_add_u64 v[186:187], s[10:11], 0, v[188:189]
	global_load_lds_dwordx4 v[186:187], off
	s_add_i32 m0, s44, 0x2000
	v_lshl_add_u64 v[186:187], s[10:11], 0, v[172:173]
	global_load_lds_dwordx4 v[186:187], off
	s_mov_b32 m0, s60
	v_lshl_add_u64 v[186:187], v[246:247], 0, s[94:95]
	global_load_lds_dwordx4 v[186:187], off
	s_mov_b32 m0, s61
	v_lshl_add_u64 v[186:187], v[248:249], 0, s[94:95]
	global_load_lds_dwordx4 v[186:187], off
	s_waitcnt vmcnt(8)
	s_waitcnt lgkmcnt(0)
	s_barrier
	s_setprio 1
	s_waitcnt lgkmcnt(0)
	v_mfma_f32_16x16x32_bf16 v[92:95], v[128:131], v[160:163], v[92:95]
	v_mfma_f32_16x16x32_bf16 v[28:31], v[136:139], v[160:163], v[28:31]
	v_mfma_f32_16x16x32_bf16 v[88:91], v[128:131], v[178:181], v[88:91]
	v_mfma_f32_16x16x32_bf16 v[24:27], v[136:139], v[178:181], v[24:27]
	v_mfma_f32_16x16x32_bf16 v[76:79], v[128:131], v[192:195], v[76:79]
	v_mfma_f32_16x16x32_bf16 v[12:15], v[136:139], v[192:195], v[12:15]
	v_mfma_f32_16x16x32_bf16 v[68:71], v[128:131], v[236:239], v[68:71]
	v_mfma_f32_16x16x32_bf16 v[4:7], v[136:139], v[236:239], v[4:7]
	v_mfma_f32_16x16x32_bf16 v[92:95], v[132:135], v[164:167], v[92:95]
	v_mfma_f32_16x16x32_bf16 v[28:31], v[140:143], v[164:167], v[28:31]
	v_mfma_f32_16x16x32_bf16 v[88:91], v[132:135], v[182:185], v[88:91]
	v_mfma_f32_16x16x32_bf16 v[24:27], v[140:143], v[182:185], v[24:27]
	v_mfma_f32_16x16x32_bf16 v[76:79], v[132:135], v[232:235], v[76:79]
	v_mfma_f32_16x16x32_bf16 v[12:15], v[140:143], v[232:235], v[12:15]
	v_mfma_f32_16x16x32_bf16 v[68:71], v[132:135], v[240:243], v[68:71]
	v_mfma_f32_16x16x32_bf16 v[4:7], v[140:143], v[240:243], v[4:7]
	s_setprio 0
	s_setprio 1
	v_mfma_f32_16x16x32_bf16 v[84:87], v[144:147], v[160:163], v[84:87]
	v_mfma_f32_16x16x32_bf16 v[20:23], v[152:155], v[160:163], v[20:23]
	v_mfma_f32_16x16x32_bf16 v[80:83], v[144:147], v[178:181], v[80:83]
	v_mfma_f32_16x16x32_bf16 v[16:19], v[152:155], v[178:181], v[16:19]
	v_mfma_f32_16x16x32_bf16 v[72:75], v[144:147], v[192:195], v[72:75]
	v_mfma_f32_16x16x32_bf16 v[8:11], v[152:155], v[192:195], v[8:11]
	v_mfma_f32_16x16x32_bf16 v[64:67], v[144:147], v[236:239], v[64:67]
	v_mfma_f32_16x16x32_bf16 v[0:3], v[152:155], v[236:239], v[0:3]
	v_mfma_f32_16x16x32_bf16 v[84:87], v[148:151], v[164:167], v[84:87]
	v_mfma_f32_16x16x32_bf16 v[20:23], v[156:159], v[164:167], v[20:23]
	v_mfma_f32_16x16x32_bf16 v[80:83], v[148:151], v[182:185], v[80:83]
	v_mfma_f32_16x16x32_bf16 v[16:19], v[156:159], v[182:185], v[16:19]
	v_mfma_f32_16x16x32_bf16 v[72:75], v[148:151], v[232:235], v[72:75]
	v_mfma_f32_16x16x32_bf16 v[8:11], v[156:159], v[232:235], v[8:11]
	v_mfma_f32_16x16x32_bf16 v[64:67], v[148:151], v[240:243], v[64:67]
	v_mfma_f32_16x16x32_bf16 v[0:3], v[156:159], v[240:243], v[0:3]
	s_setprio 0
	s_barrier
	s_add_i32 s70, s70, 2
	s_add_u32 s8, s8, 0x100
	s_addc_u32 s9, s9, 0
	s_add_u32 s46, s46, 0x100
	s_addc_u32 s47, s47, 0
	s_cmp_gt_u32 s70, 13
	s_cbranch_scc0 .LBB0_1800
	s_and_b64 vcc, exec, s[26:27]
	s_cbranch_vccz .LBB0_1803
	s_barrier

; #define PG8_STAGE(bufoff, gbase, voff) do { _Pragma("unroll") for (int _i = 0; _i < 2; ++_i) \
;         __builtin_amdgcn_global_load_lds((const unsigned*)((const char*)(gbase) + (voff)[_i]), (PG8_LAS unsigned*)(lds + (bufoff) + ldsw + _i * 8192), 16, 0, 0); } while (0)
; #define PG8_LDA(dst, b, h) do { _Pragma("unroll") for (int m = 0; m < 4; ++m) _Pragma("unroll") for (int k = 0; k < 2; ++k) dst[m][k] = *(const PG8_LAS bf16x8*)(lds + PG8_SA(b, h) + aoff + m * 2048 + k * 1024); } while (0)
; #define PG8_LDB(dst, b, h) do { _Pragma("unroll") for (int n = 0; n < 2; ++n) _Pragma("unroll") for (int k = 0; k < 2; ++k) dst[n][k] = *(const PG8_LAS bf16x8*)(lds + PG8_SB(b, h) + boff + n * 2048 + k * 1024); } while (0)
; #define PG8_MMA(ai, bj, At, Bt) do { __builtin_amdgcn_s_setprio(1); _Pragma("unroll") for (int m = 0; m < 4; ++m) _Pragma("unroll") for (int n = 0; n < 2; ++n) _Pragma("unroll") for (int k = 0; k < 2; ++k) \
;         acc[ai][bj][m][n] = __builtin_amdgcn_mfma_f32_16x16x32_bf16(Bt[n][k], At[m][k], acc[ai][bj][m][n], 0, 0, 0); __builtin_amdgcn_s_setprio(0); } while (0)
; #define PG8_WAIT_V(n) asm volatile("s_waitcnt vmcnt(" #n ")" ::: "memory")
; #define PG8_WAIT_L(n) asm volatile("s_waitcnt lgkmcnt(" #n ")" ::: "memory")
; #define PG8_BAR __builtin_amdgcn_s_barrier()
; #define PG8_SCHED __builtin_amdgcn_sched_barrier(0)
; template <class Epi, class Sched, bool ALIGN_EPI = false, bool SP2 = false>
; __device__ __forceinline__ void gemm_phase(PG8_LAS unsigned char* lds, const Gemm g, const Sched& S, const Epi& E) {
;     ...
;             const bool last = (t == nt - 2);
;             const char* a1 = cA + (size_t)(t + 1) * kstep;
;             const char* a2 = last ? nA : cA + (size_t)(t + 2) * kstep; const char* b2 = last ? nB : cB + (size_t)(t + 2) * kstep;
;             const char* a3 = a2 + kstep; const char* b3 = b2 + kstep;
;             if (last && has_next) S.a_ready(nxt);
;             if constexpr (SP2) {
;             PG8_LDB(B0, 0, 0); PG8_LDB(B1, 0, 1); PG8_SCHED; PG8_LDA(At, 0, 0); PG8_STAGE(PG8_SA(1, 1), a1 + hstepA, voffA);
;             PG8_WAIT_V(8); PG8_WAIT_L(0); PG8_BAR; PG8_MMA(0, 0, At, B0); PG8_MMA(0, 1, At, B1); PG8_BAR; PG8_SCHED;
;             PG8_LDA(At, 0, 1); PG8_STAGE(PG8_SB(0, 0), b2, voffB); PG8_STAGE(PG8_SB(0, 1), b2 + hstepB, voffB); PG8_STAGE(PG8_SA(0, 0), a2, voffA);
.LBB0_1993:
	v_add_u32_e32 v150, 0x10000, v140
	v_add_u32_e32 v166, 0x14000, v140
	ds_read_b128 v[134:137], v150
	ds_read_b128 v[142:145], v150 offset:1024
	ds_read_b128 v[146:149], v150 offset:2048
	ds_read_b128 v[150:153], v150 offset:3072
	ds_read_b128 v[154:157], v166
	ds_read_b128 v[158:161], v166 offset:1024
	ds_read_b128 v[162:165], v166 offset:2048
	ds_read_b128 v[166:169], v166 offset:3072
	ds_read_b128 v[170:173], v141
	ds_read_b128 v[174:177], v141 offset:1024
	ds_read_b128 v[178:181], v141 offset:2048
	ds_read_b128 v[182:185], v141 offset:3072
	ds_read_b128 v[192:195], v141 offset:4096
	ds_read_b128 v[230:233], v141 offset:5120
	ds_read_b128 v[234:237], v141 offset:6144
	ds_read_b128 v[238:241], v141 offset:7168
	s_add_u32 s24, s22, 0x100
	s_addc_u32 s25, s23, 0
	s_add_i32 s68, 0, 0x10000
	s_cmp_eq_u32 s67, 40
	s_cselect_b32 s29, s9, s25
	s_cselect_b32 s28, s8, s24
	s_cselect_b32 s27, s21, s66
	s_cselect_b32 s26, s20, s65
	s_add_i32 s69, 0, 0x14000
	v_lshl_add_u64 v[186:187], s[22:23], 0, v[130:131]
	s_add_i32 m0, s36, 0xc000
	global_load_lds_dwordx4 v[186:187], off
	s_add_i32 m0, s36, 0xe000
	v_lshl_add_u64 v[186:187], s[22:23], 0, v[132:133]
	global_load_lds_dwordx4 v[186:187], off
	s_waitcnt vmcnt(8)
	s_waitcnt lgkmcnt(0)
	s_barrier
	s_setprio 1
	s_waitcnt lgkmcnt(0)
	v_mfma_f32_16x16x32_bf16 v[124:127], v[134:137], v[170:173], v[124:127]
	v_mfma_f32_16x16x32_bf16 v[96:99], v[146:149], v[170:173], v[96:99]
	v_mfma_f32_16x16x32_bf16 v[120:123], v[134:137], v[178:181], v[120:123]
	v_mfma_f32_16x16x32_bf16 v[92:95], v[146:149], v[178:181], v[92:95]
	v_mfma_f32_16x16x32_bf16 v[116:119], v[134:137], v[192:195], v[116:119]
	v_mfma_f32_16x16x32_bf16 v[84:87], v[146:149], v[192:195], v[84:87]
	v_mfma_f32_16x16x32_bf16 v[112:115], v[134:137], v[234:237], v[112:115]
	v_mfma_f32_16x16x32_bf16 v[80:83], v[146:149], v[234:237], v[80:83]
	v_mfma_f32_16x16x32_bf16 v[124:127], v[142:145], v[174:177], v[124:127]
	v_mfma_f32_16x16x32_bf16 v[96:99], v[150:153], v[174:177], v[96:99]
	v_mfma_f32_16x16x32_bf16 v[120:123], v[142:145], v[182:185], v[120:123]
	v_mfma_f32_16x16x32_bf16 v[92:95], v[150:153], v[182:185], v[92:95]
	v_mfma_f32_16x16x32_bf16 v[116:119], v[142:145], v[230:233], v[116:119]
	v_mfma_f32_16x16x32_bf16 v[84:87], v[150:153], v[230:233], v[84:87]
	v_mfma_f32_16x16x32_bf16 v[112:115], v[142:145], v[238:241], v[112:115]
	v_mfma_f32_16x16x32_bf16 v[80:83], v[150:153], v[238:241], v[80:83]
	s_setprio 0
	s_setprio 1
	v_mfma_f32_16x16x32_bf16 v[64:67], v[154:157], v[170:173], v[64:67]
	v_mfma_f32_16x16x32_bf16 v[36:39], v[162:165], v[170:173], v[36:39]
	v_mfma_f32_16x16x32_bf16 v[56:59], v[154:157], v[178:181], v[56:59]
	v_mfma_f32_16x16x32_bf16 v[24:27], v[162:165], v[178:181], v[24:27]
	v_mfma_f32_16x16x32_bf16 v[52:55], v[154:157], v[192:195], v[52:55]
	v_mfma_f32_16x16x32_bf16 v[20:23], v[162:165], v[192:195], v[20:23]
	v_mfma_f32_16x16x32_bf16 v[48:51], v[154:157], v[234:237], v[48:51]
	v_mfma_f32_16x16x32_bf16 v[16:19], v[162:165], v[234:237], v[16:19]
	v_mfma_f32_16x16x32_bf16 v[64:67], v[158:161], v[174:177], v[64:67]
	v_mfma_f32_16x16x32_bf16 v[36:39], v[166:169], v[174:177], v[36:39]
	v_mfma_f32_16x16x32_bf16 v[56:59], v[158:161], v[182:185], v[56:59]
	v_mfma_f32_16x16x32_bf16 v[24:27], v[166:169], v[182:185], v[24:27]
	v_mfma_f32_16x16x32_bf16 v[52:55], v[158:161], v[230:233], v[52:55]
	v_mfma_f32_16x16x32_bf16 v[20:23], v[166:169], v[230:233], v[20:23]
	v_mfma_f32_16x16x32_bf16 v[48:51], v[158:161], v[238:241], v[48:51]
	v_mfma_f32_16x16x32_bf16 v[16:19], v[166:169], v[238:241], v[16:19]
	s_setprio 0
	s_barrier
	ds_read_b128 v[170:173], v141 offset:16384
	ds_read_b128 v[174:177], v141 offset:17408
	ds_read_b128 v[178:181], v141 offset:18432
	ds_read_b128 v[182:185], v141 offset:19456
	ds_read_b128 v[192:195], v141 offset:20480
	ds_read_b128 v[230:233], v141 offset:21504
	ds_read_b128 v[234:237], v141 offset:22528
	ds_read_b128 v[238:241], v141 offset:23552
	s_add_i32 s22, s68, s35
	v_lshl_add_u64 v[186:187], s[26:27], 0, v[188:189]
	s_mov_b32 m0, s22
	global_load_lds_dwordx4 v[186:187], off
	s_add_i32 m0, s22, 0x2000
	s_add_u32 s22, s26, 0xb0000
	v_lshl_add_u64 v[196:197], s[26:27], 0, v[128:129]
	s_addc_u32 s23, s27, 0
	s_add_i32 s68, s69, s35
	global_load_lds_dwordx4 v[196:197], off
	v_lshl_add_u64 v[242:243], s[22:23], 0, v[188:189]
	s_mov_b32 m0, s68
	v_lshl_add_u64 v[244:245], s[28:29], 0, v[128:129]
	global_load_lds_dwordx4 v[242:243], off
	s_add_i32 m0, s68, 0x2000
	v_lshl_add_u64 v[242:243], s[22:23], 0, v[128:129]
	global_load_lds_dwordx4 v[242:243], off
	s_mov_b32 m0, s36
	v_lshl_add_u64 v[242:243], s[28:29], 0, v[188:189]
	global_load_lds_dwordx4 v[242:243], off
	s_mov_b32 m0, s37
	s_nop 0
	global_load_lds_dwordx4 v[244:245], off
	s_waitcnt vmcnt(8)
	s_waitcnt lgkmcnt(0)
	s_barrier
; #define PG8_STAGE(bufoff, gbase, voff) do { _Pragma("unroll") for (int _i = 0; _i < 2; ++_i) \
;         __builtin_amdgcn_global_load_lds((const unsigned*)((const char*)(gbase) + (voff)[_i]), (PG8_LAS unsigned*)(lds + (bufoff) + ldsw + _i * 8192), 16, 0, 0); } while (0)
; #define PG8_LDA(dst, b, h) do { _Pragma("unroll") for (int m = 0; m < 4; ++m) _Pragma("unroll") for (int k = 0; k < 2; ++k) dst[m][k] = *(const PG8_LAS bf16x8*)(lds + PG8_SA(b, h) + aoff + m * 2048 + k * 1024); } while (0)
; #define PG8_LDB(dst, b, h) do { _Pragma("unroll") for (int n = 0; n < 2; ++n) _Pragma("unroll") for (int k = 0; k < 2; ++k) dst[n][k] = *(const PG8_LAS bf16x8*)(lds + PG8_SB(b, h) + boff + n * 2048 + k * 1024); } while (0)
; #define PG8_MMA(ai, bj, At, Bt) do { __builtin_amdgcn_s_setprio(1); _Pragma("unroll") for (int m = 0; m < 4; ++m) _Pragma("unroll") for (int n = 0; n < 2; ++n) _Pragma("unroll") for (int k = 0; k < 2; ++k) \
;         acc[ai][bj][m][n] = __builtin_amdgcn_mfma_f32_16x16x32_bf16(Bt[n][k], At[m][k], acc[ai][bj][m][n], 0, 0, 0); __builtin_amdgcn_s_setprio(0); } while (0)
; #define PG8_WAIT_V(n) asm volatile("s_waitcnt vmcnt(" #n ")" ::: "memory")
; #define PG8_WAIT_L(n) asm volatile("s_waitcnt lgkmcnt(" #n ")" ::: "memory")
; #define PG8_BAR __builtin_amdgcn_s_barrier()
; #define PG8_SCHED __builtin_amdgcn_sched_barrier(0)
; template <class Epi, class Sched, bool ALIGN_EPI = false, bool SP2 = false>
; __device__ __forceinline__ void gemm_phase(PG8_LAS unsigned char* lds, const Gemm g, const Sched& S, const Epi& E) {
;     ...
;             PG8_WAIT_V(8); PG8_WAIT_L(0); PG8_BAR; PG8_MMA(1, 0, At, B0); PG8_MMA(1, 1, At, B1); PG8_BAR; PG8_SCHED;
;             PG8_LDB(B0, 1, 0); PG8_LDB(B1, 1, 1); PG8_SCHED; PG8_LDA(At, 1, 0); PG8_STAGE(PG8_SA(0, 1), a2 + hstepA, voffA);
;             PG8_WAIT_V(8); PG8_WAIT_L(0); PG8_BAR; PG8_MMA(0, 0, At, B0); PG8_MMA(0, 1, At, B1); PG8_BAR; PG8_SCHED;
	s_setprio 1
	s_waitcnt lgkmcnt(0)
	v_mfma_f32_16x16x32_bf16 v[108:111], v[134:137], v[170:173], v[108:111]
	v_mfma_f32_16x16x32_bf16 v[76:79], v[146:149], v[170:173], v[76:79]
	v_mfma_f32_16x16x32_bf16 v[104:107], v[134:137], v[178:181], v[104:107]
	v_mfma_f32_16x16x32_bf16 v[72:75], v[146:149], v[178:181], v[72:75]
	v_mfma_f32_16x16x32_bf16 v[100:103], v[134:137], v[192:195], v[100:103]
	v_mfma_f32_16x16x32_bf16 v[68:71], v[146:149], v[192:195], v[68:71]
	v_mfma_f32_16x16x32_bf16 v[88:91], v[134:137], v[234:237], v[88:91]
	v_mfma_f32_16x16x32_bf16 v[60:63], v[146:149], v[234:237], v[60:63]
	v_mfma_f32_16x16x32_bf16 v[108:111], v[142:145], v[174:177], v[108:111]
	v_mfma_f32_16x16x32_bf16 v[76:79], v[150:153], v[174:177], v[76:79]
	v_mfma_f32_16x16x32_bf16 v[104:107], v[142:145], v[182:185], v[104:107]
	v_mfma_f32_16x16x32_bf16 v[72:75], v[150:153], v[182:185], v[72:75]
	v_mfma_f32_16x16x32_bf16 v[100:103], v[142:145], v[230:233], v[100:103]
	v_mfma_f32_16x16x32_bf16 v[68:71], v[150:153], v[230:233], v[68:71]
	v_mfma_f32_16x16x32_bf16 v[88:91], v[142:145], v[238:241], v[88:91]
	v_mfma_f32_16x16x32_bf16 v[60:63], v[150:153], v[238:241], v[60:63]
	s_setprio 0
	s_setprio 1
	v_mfma_f32_16x16x32_bf16 v[44:47], v[154:157], v[170:173], v[44:47]
	v_mfma_f32_16x16x32_bf16 v[12:15], v[162:165], v[170:173], v[12:15]
	v_mfma_f32_16x16x32_bf16 v[40:43], v[154:157], v[178:181], v[40:43]
	v_mfma_f32_16x16x32_bf16 v[8:11], v[162:165], v[178:181], v[8:11]
	v_mfma_f32_16x16x32_bf16 v[32:35], v[154:157], v[192:195], v[32:35]
	v_mfma_f32_16x16x32_bf16 v[4:7], v[162:165], v[192:195], v[4:7]
	v_mfma_f32_16x16x32_bf16 v[28:31], v[154:157], v[234:237], v[28:31]
	v_mfma_f32_16x16x32_bf16 v[0:3], v[162:165], v[234:237], v[0:3]
	v_mfma_f32_16x16x32_bf16 v[44:47], v[158:161], v[174:177], v[44:47]
	v_mfma_f32_16x16x32_bf16 v[12:15], v[166:169], v[174:177], v[12:15]
	v_mfma_f32_16x16x32_bf16 v[40:43], v[158:161], v[182:185], v[40:43]
	v_mfma_f32_16x16x32_bf16 v[8:11], v[166:169], v[182:185], v[8:11]
	v_mfma_f32_16x16x32_bf16 v[32:35], v[158:161], v[230:233], v[32:35]
	v_mfma_f32_16x16x32_bf16 v[4:7], v[166:169], v[230:233], v[4:7]
	v_mfma_f32_16x16x32_bf16 v[28:31], v[158:161], v[238:241], v[28:31]
	v_mfma_f32_16x16x32_bf16 v[0:3], v[166:169], v[238:241], v[0:3]
	s_setprio 0
	s_barrier
	v_add_u32_e32 v150, 0x18000, v140
	v_add_u32_e32 v166, 0x1c000, v140
	ds_read_b128 v[134:137], v150
	ds_read_b128 v[142:145], v150 offset:1024
	ds_read_b128 v[146:149], v150 offset:2048
	ds_read_b128 v[150:153], v150 offset:3072
	ds_read_b128 v[154:157], v166
	ds_read_b128 v[158:161], v166 offset:1024
	ds_read_b128 v[162:165], v166 offset:2048
	ds_read_b128 v[166:169], v166 offset:3072
	ds_read_b128 v[170:173], v141 offset:32768
	ds_read_b128 v[174:177], v141 offset:33792
	ds_read_b128 v[178:181], v141 offset:34816
	ds_read_b128 v[182:185], v141 offset:35840
	ds_read_b128 v[192:195], v141 offset:36864
	ds_read_b128 v[230:233], v141 offset:37888
	ds_read_b128 v[234:237], v141 offset:38912
	ds_read_b128 v[238:241], v141 offset:39936
	s_add_i32 s68, 0, 0x18000
	s_add_i32 s69, 0, 0x1c000
	s_add_u32 s22, s28, 0xb0000
	s_addc_u32 s23, s29, 0
	s_mov_b32 m0, s44
	v_lshl_add_u64 v[246:247], s[22:23], 0, v[188:189]
	global_load_lds_dwordx4 v[246:247], off
	s_mov_b32 m0, s45
	v_lshl_add_u64 v[246:247], s[22:23], 0, v[128:129]
	global_load_lds_dwordx4 v[246:247], off
	s_waitcnt vmcnt(8)
	s_waitcnt lgkmcnt(0)
	s_barrier
	s_setprio 1
	s_waitcnt lgkmcnt(0)
	v_mfma_f32_16x16x32_bf16 v[124:127], v[134:137], v[170:173], v[124:127]
	v_mfma_f32_16x16x32_bf16 v[96:99], v[146:149], v[170:173], v[96:99]
	v_mfma_f32_16x16x32_bf16 v[120:123], v[134:137], v[178:181], v[120:123]
	v_mfma_f32_16x16x32_bf16 v[92:95], v[146:149], v[178:181], v[92:95]
	v_mfma_f32_16x16x32_bf16 v[116:119], v[134:137], v[192:195], v[116:119]
	v_mfma_f32_16x16x32_bf16 v[84:87], v[146:149], v[192:195], v[84:87]
	v_mfma_f32_16x16x32_bf16 v[112:115], v[134:137], v[234:237], v[112:115]
	v_mfma_f32_16x16x32_bf16 v[80:83], v[146:149], v[234:237], v[80:83]
	v_mfma_f32_16x16x32_bf16 v[124:127], v[142:145], v[174:177], v[124:127]
	v_mfma_f32_16x16x32_bf16 v[96:99], v[150:153], v[174:177], v[96:99]
	v_mfma_f32_16x16x32_bf16 v[120:123], v[142:145], v[182:185], v[120:123]
	v_mfma_f32_16x16x32_bf16 v[92:95], v[150:153], v[182:185], v[92:95]
	v_mfma_f32_16x16x32_bf16 v[116:119], v[142:145], v[230:233], v[116:119]
	v_mfma_f32_16x16x32_bf16 v[84:87], v[150:153], v[230:233], v[84:87]
	v_mfma_f32_16x16x32_bf16 v[112:115], v[142:145], v[238:241], v[112:115]
	v_mfma_f32_16x16x32_bf16 v[80:83], v[150:153], v[238:241], v[80:83]
	s_setprio 0
	s_setprio 1
	v_mfma_f32_16x16x32_bf16 v[64:67], v[154:157], v[170:173], v[64:67]
	v_mfma_f32_16x16x32_bf16 v[36:39], v[162:165], v[170:173], v[36:39]
	v_mfma_f32_16x16x32_bf16 v[56:59], v[154:157], v[178:181], v[56:59]
	v_mfma_f32_16x16x32_bf16 v[24:27], v[162:165], v[178:181], v[24:27]
	v_mfma_f32_16x16x32_bf16 v[52:55], v[154:157], v[192:195], v[52:55]
	v_mfma_f32_16x16x32_bf16 v[20:23], v[162:165], v[192:195], v[20:23]
	v_mfma_f32_16x16x32_bf16 v[48:51], v[154:157], v[234:237], v[48:51]
	v_mfma_f32_16x16x32_bf16 v[16:19], v[162:165], v[234:237], v[16:19]
	v_mfma_f32_16x16x32_bf16 v[64:67], v[158:161], v[174:177], v[64:67]
	v_mfma_f32_16x16x32_bf16 v[36:39], v[166:169], v[174:177], v[36:39]
	v_mfma_f32_16x16x32_bf16 v[56:59], v[158:161], v[182:185], v[56:59]
	v_mfma_f32_16x16x32_bf16 v[24:27], v[166:169], v[182:185], v[24:27]
	v_mfma_f32_16x16x32_bf16 v[52:55], v[158:161], v[230:233], v[52:55]
	v_mfma_f32_16x16x32_bf16 v[20:23], v[166:169], v[230:233], v[20:23]
	v_mfma_f32_16x16x32_bf16 v[48:51], v[158:161], v[238:241], v[48:51]
	v_mfma_f32_16x16x32_bf16 v[16:19], v[166:169], v[238:241], v[16:19]
	s_setprio 0
	s_barrier
; #define PG8_STAGE(bufoff, gbase, voff) do { _Pragma("unroll") for (int _i = 0; _i < 2; ++_i) \
;         __builtin_amdgcn_global_load_lds((const unsigned*)((const char*)(gbase) + (voff)[_i]), (PG8_LAS unsigned*)(lds + (bufoff) + ldsw + _i * 8192), 16, 0, 0); } while (0)
; #define PG8_LDA(dst, b, h) do { _Pragma("unroll") for (int m = 0; m < 4; ++m) _Pragma("unroll") for (int k = 0; k < 2; ++k) dst[m][k] = *(const PG8_LAS bf16x8*)(lds + PG8_SA(b, h) + aoff + m * 2048 + k * 1024); } while (0)
; #define PG8_MMA(ai, bj, At, Bt) do { __builtin_amdgcn_s_setprio(1); _Pragma("unroll") for (int m = 0; m < 4; ++m) _Pragma("unroll") for (int n = 0; n < 2; ++n) _Pragma("unroll") for (int k = 0; k < 2; ++k) \
;         acc[ai][bj][m][n] = __builtin_amdgcn_mfma_f32_16x16x32_bf16(Bt[n][k], At[m][k], acc[ai][bj][m][n], 0, 0, 0); __builtin_amdgcn_s_setprio(0); } while (0)
; #define PG8_WAIT_V(n) asm volatile("s_waitcnt vmcnt(" #n ")" ::: "memory")
; #define PG8_WAIT_L(n) asm volatile("s_waitcnt lgkmcnt(" #n ")" ::: "memory")
; #define PG8_BAR __builtin_amdgcn_s_barrier()
; #define PG8_SCHED __builtin_amdgcn_sched_barrier(0)
; template <class Epi, class Sched, bool ALIGN_EPI = false, bool SP2 = false>
; __device__ __forceinline__ void gemm_phase(PG8_LAS unsigned char* lds, const Gemm g, const Sched& S, const Epi& E) {
;     ...
;         for (int t = 0; t < nt; t += 2) {
;     ...
;             PG8_LDA(At, 1, 1); PG8_STAGE(PG8_SB(1, 0), b3, voffB); PG8_STAGE(PG8_SB(1, 1), b3 + hstepB, voffB); PG8_STAGE(PG8_SA(1, 0), a3, voffA);
;             PG8_WAIT_V(8); PG8_WAIT_L(0); PG8_BAR; PG8_MMA(1, 0, At, B0); PG8_MMA(1, 1, At, B1); PG8_BAR; PG8_SCHED;
	ds_read_b128 v[170:173], v141 offset:49152
	ds_read_b128 v[174:177], v141 offset:50176
	ds_read_b128 v[178:181], v141 offset:51200
	ds_read_b128 v[182:185], v141 offset:52224
	ds_read_b128 v[192:195], v141 offset:53248
	ds_read_b128 v[230:233], v141 offset:54272
	ds_read_b128 v[234:237], v141 offset:55296
	ds_read_b128 v[238:241], v141 offset:56320
	s_add_i32 s22, s68, s35
	v_lshl_add_u64 v[186:187], v[186:187], 0, s[94:95]
	s_mov_b32 m0, s22
	global_load_lds_dwordx4 v[186:187], off
	s_add_i32 m0, s22, 0x2000
	s_add_u32 s22, s26, 0xb0080
	v_lshl_add_u64 v[186:187], v[196:197], 0, s[94:95]
	s_addc_u32 s23, s27, 0
	s_add_i32 s26, s69, s35
	global_load_lds_dwordx4 v[186:187], off
	s_mov_b32 m0, s26
	v_lshl_add_u64 v[186:187], s[22:23], 0, v[188:189]
	global_load_lds_dwordx4 v[186:187], off
	s_add_i32 m0, s26, 0x2000
	v_lshl_add_u64 v[186:187], s[22:23], 0, v[128:129]
	global_load_lds_dwordx4 v[186:187], off
	s_mov_b32 m0, s57
	v_lshl_add_u64 v[186:187], v[242:243], 0, s[94:95]
	global_load_lds_dwordx4 v[186:187], off
	s_mov_b32 m0, s58
	v_lshl_add_u64 v[186:187], v[244:245], 0, s[94:95]
	global_load_lds_dwordx4 v[186:187], off
	s_waitcnt vmcnt(8)
	s_waitcnt lgkmcnt(0)
	s_barrier
	s_setprio 1
	s_waitcnt lgkmcnt(0)
	v_mfma_f32_16x16x32_bf16 v[108:111], v[134:137], v[170:173], v[108:111]
	v_mfma_f32_16x16x32_bf16 v[76:79], v[146:149], v[170:173], v[76:79]
	v_mfma_f32_16x16x32_bf16 v[104:107], v[134:137], v[178:181], v[104:107]
	v_mfma_f32_16x16x32_bf16 v[72:75], v[146:149], v[178:181], v[72:75]
	v_mfma_f32_16x16x32_bf16 v[100:103], v[134:137], v[192:195], v[100:103]
	v_mfma_f32_16x16x32_bf16 v[68:71], v[146:149], v[192:195], v[68:71]
	v_mfma_f32_16x16x32_bf16 v[88:91], v[134:137], v[234:237], v[88:91]
	v_mfma_f32_16x16x32_bf16 v[60:63], v[146:149], v[234:237], v[60:63]
	v_mfma_f32_16x16x32_bf16 v[108:111], v[142:145], v[174:177], v[108:111]
	v_mfma_f32_16x16x32_bf16 v[76:79], v[150:153], v[174:177], v[76:79]
	v_mfma_f32_16x16x32_bf16 v[104:107], v[142:145], v[182:185], v[104:107]
	v_mfma_f32_16x16x32_bf16 v[72:75], v[150:153], v[182:185], v[72:75]
	v_mfma_f32_16x16x32_bf16 v[100:103], v[142:145], v[230:233], v[100:103]
	v_mfma_f32_16x16x32_bf16 v[68:71], v[150:153], v[230:233], v[68:71]
	v_mfma_f32_16x16x32_bf16 v[88:91], v[142:145], v[238:241], v[88:91]
	v_mfma_f32_16x16x32_bf16 v[60:63], v[150:153], v[238:241], v[60:63]
	s_setprio 0
	s_setprio 1
	v_mfma_f32_16x16x32_bf16 v[44:47], v[154:157], v[170:173], v[44:47]
	v_mfma_f32_16x16x32_bf16 v[12:15], v[162:165], v[170:173], v[12:15]
	v_mfma_f32_16x16x32_bf16 v[40:43], v[154:157], v[178:181], v[40:43]
	v_mfma_f32_16x16x32_bf16 v[8:11], v[162:165], v[178:181], v[8:11]
	v_mfma_f32_16x16x32_bf16 v[32:35], v[154:157], v[192:195], v[32:35]
	v_mfma_f32_16x16x32_bf16 v[4:7], v[162:165], v[192:195], v[4:7]
	v_mfma_f32_16x16x32_bf16 v[28:31], v[154:157], v[234:237], v[28:31]
	v_mfma_f32_16x16x32_bf16 v[0:3], v[162:165], v[234:237], v[0:3]
	v_mfma_f32_16x16x32_bf16 v[44:47], v[158:161], v[174:177], v[44:47]
	v_mfma_f32_16x16x32_bf16 v[12:15], v[166:169], v[174:177], v[12:15]
	v_mfma_f32_16x16x32_bf16 v[40:43], v[158:161], v[182:185], v[40:43]
	v_mfma_f32_16x16x32_bf16 v[8:11], v[166:169], v[182:185], v[8:11]
	v_mfma_f32_16x16x32_bf16 v[32:35], v[158:161], v[230:233], v[32:35]
	v_mfma_f32_16x16x32_bf16 v[4:7], v[166:169], v[230:233], v[4:7]
	v_mfma_f32_16x16x32_bf16 v[28:31], v[158:161], v[238:241], v[28:31]
	v_mfma_f32_16x16x32_bf16 v[0:3], v[166:169], v[238:241], v[0:3]
	s_setprio 0
	s_barrier
	s_add_i32 s67, s67, 2
	s_add_u32 s65, s65, 0x100
	s_addc_u32 s66, s66, 0
	s_cmp_gt_u32 s67, 41
	s_mov_b64 s[22:23], s[24:25]
	s_cbranch_scc0 .LBB0_1993
	s_and_b64 vcc, exec, s[14:15]
	s_cbranch_vccz .LBB0_1996
	s_barrier
